# ffn_up epilogue conv part rewritten: fmac_dpp taps, in-place scaling, 16-byte ACT stores
# speedup vs baseline: 1.0101x; 1.0078x over previous
; #define PG8_LAS __attribute__((address_space(3)))
;     __device__ __forceinline__ void operator()(const f32x4 (&acc)[2][2][4][2], const Unit& u, int wr, int wc, int fr, int fq) const {
;     ...
;         asm volatile("s_waitcnt lgkmcnt(0)" ::: "memory"); __builtin_amdgcn_s_barrier(); asm volatile("" ::: "memory");
; #pragma unroll
;         for (int n = 0; n < 2; ++n) {
;             f32x4 w[2][3];
; #pragma unroll
;             for (int bj = 0; bj < 2; ++bj)
; #pragma unroll
;                 for (int j = 0; j < 3; ++j) w[bj][j] = *(const f32x4*)(cw + j * 11264 + bj * 5632 + u.pn * 128 + cidx + 4 * n);
; #pragma unroll
;             for (int ai = 0; ai < 2; ++ai) {
;                 const int gi = ai * 2 + wr;
;                 f32x4 o1[2], o2[2];
; #pragma unroll
;                 for (int bj = 0; bj < 2; ++bj) {
;                     o1[bj] = (f32x4){0.f, 0.f, 0.f, 0.f}; o2[bj] = o1[bj];
;                     if (gi > 0) { o1[bj] = *(const PG8_LAS f32x4*)(xch + (((((gi - 1) * 2 + 1) * 2 + bj) * 128) + cidx + 4 * n) * 4);
;                                   o2[bj] = *(const PG8_LAS f32x4*)(xch + (((((gi - 1) * 2 + (fr == 0 ? 0 : 1)) * 2 + bj) * 128) + cidx + 4 * n) * 4); }
;                 }
; #pragma unroll
;                 for (int m = 0; m < 4; ++m) {
;                     f32x4 uu[2];
; #pragma unroll
;                     for (int bj = 0; bj < 2; ++bj) { const f32x4 cur = acc[ai][bj][m][n] * rs[ai][m];
; #pragma unroll
;                         for (int q = 0; q < 4; ++q) { const float p1 = dpp_shr1(o1[bj][q], cur[q]), p2 = dpp_shr2(o2[bj][q], cur[q]);
;                             uu[bj][q] = w[bj][0][q] * p2 + w[bj][1][q] * p1 + w[bj][2][q] * cur[q];
;                             o1[bj][q] = dpp_ror1(cur[q]); o2[bj][q] = dpp_ror2(cur[q]); } }
;                     u32x2v o;
;                     { const float a0 = uu[0][0] * __builtin_amdgcn_rcpf(1.f + __expf(-uu[0][0])) * uu[1][0], a1 = uu[0][1] * __builtin_amdgcn_rcpf(1.f + __expf(-uu[0][1])) * uu[1][1];
;                       const float a2 = uu[0][2] * __builtin_amdgcn_rcpf(1.f + __expf(-uu[0][2])) * uu[1][2], a3 = uu[0][3] * __builtin_amdgcn_rcpf(1.f + __expf(-uu[0][3])) * uu[1][3];
;                       o.x = cvt_pk_bf16(a0, a1); o.y = cvt_pk_bf16(a2, a3); }
;                     *(u32x2v*)(ACT + (size_t)(row0 + ai * HALF + m * 16) * 5632 + u.pn * 128 + cidx + 4 * n) = o;
.LBB0_1910:
	s_or_b64 exec, exec, s[8:9]
	v_lshl_add_u64 v[222:223], s[10:11], 2, v[186:187]
	s_waitcnt lgkmcnt(0)
	s_barrier
	s_mov_b32 s9, 0
	global_load_dwordx4 v[130:133], v[222:223], off
	s_mov_b32 s8, 0xb000
	v_lshl_add_u64 v[234:235], v[222:223], 0, s[8:9]
	global_load_dwordx4 v[134:137], v[234:235], off
	s_mov_b32 s8, 0x16000
	v_lshl_add_u64 v[234:235], v[222:223], 0, s[8:9]
	global_load_dwordx4 v[138:141], v[234:235], off
	s_mov_b32 s8, 0x5800
	v_lshl_add_u64 v[234:235], v[222:223], 0, s[8:9]
	global_load_dwordx4 v[142:145], v[234:235], off
	s_mov_b32 s8, 0x10800
	v_lshl_add_u64 v[234:235], v[222:223], 0, s[8:9]
	global_load_dwordx4 v[146:149], v[234:235], off
	s_mov_b32 s8, 0x1b800
	v_lshl_add_u64 v[234:235], v[222:223], 0, s[8:9]
	global_load_dwordx4 v[150:153], v[234:235], off
	v_add_f32_e32 v214, v214, v215
	v_add_f32_e32 v218, v219, v225
	v_add_f32_e32 v202, v199, v211
	v_add_f32_e32 v204, v209, v213
	v_fmamk_f32 v214, v214, 0x3a000000, v241
	v_fmamk_f32 v218, v218, 0x3a000000, v241
	v_fmamk_f32 v202, v202, 0x3a000000, v241
	v_fmamk_f32 v204, v204, 0x3a000000, v241
	v_rsq_f32_e32 v214, v214
	v_rsq_f32_e32 v218, v218
	v_rsq_f32_e32 v202, v202
	v_rsq_f32_e32 v204, v204
	v_mov_b64_e32 v[234:235], s[14:15]
	v_mad_i64_i32 v[246:247], s[12:13], v228, s53, v[234:235]
	s_lshl_b64 s[74:75], s[10:11], 1
	v_lshl_add_u64 v[246:247], v[246:247], 0, s[74:75]
	v_lshlrev_b32_e32 v128, 1, v180
	v_lshl_add_u64 v[246:247], v[246:247], 0, v[128:129]
	s_and_b32 s8, s28, 0x800
	s_add_i32 s8, s8, s91
	s_addk_i32 s8, 0xf800
	v_add_u32_e32 v195, s8, v184
	v_cmp_eq_u32_e32 vcc, 14, v178
	v_add_u32_e32 v197, 0x400, v195
	v_cndmask_b32_e32 v197, v197, v195, vcc
	s_cmp_eq_u32 s28, 0
	s_cbranch_scc1 .Lupc_zero_b0
	ds_read_b128 v[154:157], v197
	ds_read_b128 v[158:161], v197 offset:512
	s_branch .Lupc_go_b0
.Lupc_zero_b0:
	v_mov_b32_e32 v154, 0
	v_mov_b32_e32 v155, 0
	v_mov_b32_e32 v156, 0
	v_mov_b32_e32 v157, 0
	v_mov_b32_e32 v158, 0
	v_mov_b32_e32 v159, 0
	v_mov_b32_e32 v160, 0
	v_mov_b32_e32 v161, 0
.Lupc_go_b0:
	s_waitcnt vmcnt(0)
	s_waitcnt lgkmcnt(0)
	v_pk_mul_f32 v[124:125], v[124:125], v[210:211] op_sel_hi:[1,0]
	v_pk_mul_f32 v[126:127], v[126:127], v[210:211] op_sel_hi:[1,0]
	v_pk_mul_f32 v[120:121], v[120:121], v[210:211] op_sel_hi:[1,0]
	v_pk_mul_f32 v[122:123], v[122:123], v[210:211] op_sel_hi:[1,0]
	v_pk_mul_f32 v[162:163], v[124:125], v[138:139]
	v_pk_mul_f32 v[164:165], v[126:127], v[140:141]
	v_pk_mul_f32 v[166:167], v[120:121], v[150:151]
	v_pk_mul_f32 v[168:169], v[122:123], v[152:153]
	v_fmac_f32_dpp v162, v124, v134 row_shr:1 row_mask:0xf bank_mask:0xf
	v_fmac_f32_dpp v163, v125, v135 row_shr:1 row_mask:0xf bank_mask:0xf
	v_fmac_f32_dpp v164, v126, v136 row_shr:1 row_mask:0xf bank_mask:0xf
	v_fmac_f32_dpp v165, v127, v137 row_shr:1 row_mask:0xf bank_mask:0xf
	v_fmac_f32_dpp v166, v120, v146 row_shr:1 row_mask:0xf bank_mask:0xf
	v_fmac_f32_dpp v167, v121, v147 row_shr:1 row_mask:0xf bank_mask:0xf
	v_fmac_f32_dpp v168, v122, v148 row_shr:1 row_mask:0xf bank_mask:0xf
	v_fmac_f32_dpp v169, v123, v149 row_shr:1 row_mask:0xf bank_mask:0xf
	v_fmac_f32_dpp v162, v124, v130 row_shr:2 row_mask:0xf bank_mask:0xf
	v_fmac_f32_dpp v163, v125, v131 row_shr:2 row_mask:0xf bank_mask:0xf
	v_fmac_f32_dpp v164, v126, v132 row_shr:2 row_mask:0xf bank_mask:0xf
	v_fmac_f32_dpp v165, v127, v133 row_shr:2 row_mask:0xf bank_mask:0xf
	v_fmac_f32_dpp v166, v120, v142 row_shr:2 row_mask:0xf bank_mask:0xf
	v_fmac_f32_dpp v167, v121, v143 row_shr:2 row_mask:0xf bank_mask:0xf
	v_fmac_f32_dpp v168, v122, v144 row_shr:2 row_mask:0xf bank_mask:0xf
	v_fmac_f32_dpp v169, v123, v145 row_shr:2 row_mask:0xf bank_mask:0xf
	v_fmac_f32_dpp v162, v154, v134 row_shl:15 row_mask:0xf bank_mask:0xf
	v_fmac_f32_dpp v163, v155, v135 row_shl:15 row_mask:0xf bank_mask:0xf
	v_fmac_f32_dpp v164, v156, v136 row_shl:15 row_mask:0xf bank_mask:0xf
	v_fmac_f32_dpp v165, v157, v137 row_shl:15 row_mask:0xf bank_mask:0xf
	v_fmac_f32_dpp v166, v158, v146 row_shl:15 row_mask:0xf bank_mask:0xf
	v_fmac_f32_dpp v167, v159, v147 row_shl:15 row_mask:0xf bank_mask:0xf
	v_fmac_f32_dpp v168, v160, v148 row_shl:15 row_mask:0xf bank_mask:0xf
	v_fmac_f32_dpp v169, v161, v149 row_shl:15 row_mask:0xf bank_mask:0xf
	v_fmac_f32_dpp v162, v154, v130 row_shl:14 row_mask:0xf bank_mask:0xf
	v_fmac_f32_dpp v163, v155, v131 row_shl:14 row_mask:0xf bank_mask:0xf
	v_fmac_f32_dpp v164, v156, v132 row_shl:14 row_mask:0xf bank_mask:0xf
	v_fmac_f32_dpp v165, v157, v133 row_shl:14 row_mask:0xf bank_mask:0xf
	v_fmac_f32_dpp v166, v158, v142 row_shl:14 row_mask:0xf bank_mask:0xf
	v_fmac_f32_dpp v167, v159, v143 row_shl:14 row_mask:0xf bank_mask:0xf
	v_fmac_f32_dpp v168, v160, v144 row_shl:14 row_mask:0xf bank_mask:0xf
	v_fmac_f32_dpp v169, v161, v145 row_shl:14 row_mask:0xf bank_mask:0xf
	v_mul_f32_e32 v230, 0xbfb8aa3b, v162
	v_mul_f32_e32 v231, 0xbfb8aa3b, v163
	v_mul_f32_e32 v232, 0xbfb8aa3b, v164
	v_mul_f32_e32 v233, 0xbfb8aa3b, v165
	v_exp_f32_e32 v230, v230
	v_exp_f32_e32 v231, v231
	v_exp_f32_e32 v232, v232
	v_exp_f32_e32 v233, v233
	v_add_f32_e32 v230, 1.0, v230
	v_add_f32_e32 v231, 1.0, v231
	v_add_f32_e32 v232, 1.0, v232
	v_add_f32_e32 v233, 1.0, v233
	v_rcp_f32_e32 v230, v230
	v_rcp_f32_e32 v231, v231
	v_rcp_f32_e32 v232, v232
	v_rcp_f32_e32 v233, v233
	v_mul_f32_e32 v230, v162, v230
	v_mul_f32_e32 v231, v163, v231
	v_mul_f32_e32 v232, v164, v232
	v_mul_f32_e32 v233, v165, v233
	v_mul_f32_e32 v230, v230, v166
	v_mul_f32_e32 v231, v231, v167
	v_mul_f32_e32 v232, v232, v168
	v_mul_f32_e32 v233, v233, v169
	v_cvt_pk_bf16_f32 v224, v230, v231
	v_cvt_pk_bf16_f32 v225, v232, v233
	ds_read_b128 v[154:157], v197 offset:4096
; #define PG8_LAS __attribute__((address_space(3)))
; __device__ __forceinline__ unsigned cvt_pk_bf16(float lo, float hi) { unsigned r; asm volatile("v_cvt_pk_bf16_f32 %0, %1, %2" : "=v"(r) : "v"(lo), "v"(hi)); return r; }
;     static __device__ __forceinline__ float dpp_shr1(float old, float src) { return __builtin_bit_cast(float, __builtin_amdgcn_update_dpp(__builtin_bit_cast(int, old), __builtin_bit_cast(int, src), 0x111, 0xf, 0xf, false)); }
;     static __device__ __forceinline__ float dpp_shr2(float old, float src) { return __builtin_bit_cast(float, __builtin_amdgcn_update_dpp(__builtin_bit_cast(int, old), __builtin_bit_cast(int, src), 0x112, 0xf, 0xf, false)); }
;     __device__ __forceinline__ void operator()(const f32x4 (&acc)[2][2][4][2], const Unit& u, int wr, int wc, int fr, int fq) const {
;     ...
;                 for (int bj = 0; bj < 2; ++bj) {
;                     o1[bj] = (f32x4){0.f, 0.f, 0.f, 0.f}; o2[bj] = o1[bj];
;                     if (gi > 0) { o1[bj] = *(const PG8_LAS f32x4*)(xch + (((((gi - 1) * 2 + 1) * 2 + bj) * 128) + cidx + 4 * n) * 4);
;                                   o2[bj] = *(const PG8_LAS f32x4*)(xch + (((((gi - 1) * 2 + (fr == 0 ? 0 : 1)) * 2 + bj) * 128) + cidx + 4 * n) * 4); }
;                 }
; #pragma unroll
;                 for (int m = 0; m < 4; ++m) {
;                     f32x4 uu[2];
; #pragma unroll
;                     for (int bj = 0; bj < 2; ++bj) { const f32x4 cur = acc[ai][bj][m][n] * rs[ai][m];
; #pragma unroll
;                         for (int q = 0; q < 4; ++q) { const float p1 = dpp_shr1(o1[bj][q], cur[q]), p2 = dpp_shr2(o2[bj][q], cur[q]);
;                             uu[bj][q] = w[bj][0][q] * p2 + w[bj][1][q] * p1 + w[bj][2][q] * cur[q];
;                             o1[bj][q] = dpp_ror1(cur[q]); o2[bj][q] = dpp_ror2(cur[q]); } }
;                     u32x2v o;
;                     { const float a0 = uu[0][0] * __builtin_amdgcn_rcpf(1.f + __expf(-uu[0][0])) * uu[1][0], a1 = uu[0][1] * __builtin_amdgcn_rcpf(1.f + __expf(-uu[0][1])) * uu[1][1];
;                       const float a2 = uu[0][2] * __builtin_amdgcn_rcpf(1.f + __expf(-uu[0][2])) * uu[1][2], a3 = uu[0][3] * __builtin_amdgcn_rcpf(1.f + __expf(-uu[0][3])) * uu[1][3];
;                       o.x = cvt_pk_bf16(a0, a1); o.y = cvt_pk_bf16(a2, a3); }
	ds_read_b128 v[158:161], v197 offset:4608
	v_pk_mul_f32 v[116:117], v[116:117], v[214:215] op_sel_hi:[1,0]
	v_pk_mul_f32 v[118:119], v[118:119], v[214:215] op_sel_hi:[1,0]
	v_pk_mul_f32 v[112:113], v[112:113], v[214:215] op_sel_hi:[1,0]
	v_pk_mul_f32 v[114:115], v[114:115], v[214:215] op_sel_hi:[1,0]
	v_pk_mul_f32 v[162:163], v[116:117], v[138:139]
	v_pk_mul_f32 v[164:165], v[118:119], v[140:141]
	v_pk_mul_f32 v[166:167], v[112:113], v[150:151]
	v_pk_mul_f32 v[168:169], v[114:115], v[152:153]
	v_fmac_f32_dpp v162, v116, v134 row_shr:1 row_mask:0xf bank_mask:0xf
	v_fmac_f32_dpp v163, v117, v135 row_shr:1 row_mask:0xf bank_mask:0xf
	v_fmac_f32_dpp v164, v118, v136 row_shr:1 row_mask:0xf bank_mask:0xf
	v_fmac_f32_dpp v165, v119, v137 row_shr:1 row_mask:0xf bank_mask:0xf
	v_fmac_f32_dpp v166, v112, v146 row_shr:1 row_mask:0xf bank_mask:0xf
	v_fmac_f32_dpp v167, v113, v147 row_shr:1 row_mask:0xf bank_mask:0xf
	v_fmac_f32_dpp v168, v114, v148 row_shr:1 row_mask:0xf bank_mask:0xf
	v_fmac_f32_dpp v169, v115, v149 row_shr:1 row_mask:0xf bank_mask:0xf
	v_fmac_f32_dpp v162, v116, v130 row_shr:2 row_mask:0xf bank_mask:0xf
	v_fmac_f32_dpp v163, v117, v131 row_shr:2 row_mask:0xf bank_mask:0xf
	v_fmac_f32_dpp v164, v118, v132 row_shr:2 row_mask:0xf bank_mask:0xf
	v_fmac_f32_dpp v165, v119, v133 row_shr:2 row_mask:0xf bank_mask:0xf
	v_fmac_f32_dpp v166, v112, v142 row_shr:2 row_mask:0xf bank_mask:0xf
	v_fmac_f32_dpp v167, v113, v143 row_shr:2 row_mask:0xf bank_mask:0xf
	v_fmac_f32_dpp v168, v114, v144 row_shr:2 row_mask:0xf bank_mask:0xf
	v_fmac_f32_dpp v169, v115, v145 row_shr:2 row_mask:0xf bank_mask:0xf
	v_fmac_f32_dpp v162, v124, v134 row_shl:15 row_mask:0xf bank_mask:0xf
	v_fmac_f32_dpp v163, v125, v135 row_shl:15 row_mask:0xf bank_mask:0xf
	v_fmac_f32_dpp v164, v126, v136 row_shl:15 row_mask:0xf bank_mask:0xf
	v_fmac_f32_dpp v165, v127, v137 row_shl:15 row_mask:0xf bank_mask:0xf
	v_fmac_f32_dpp v166, v120, v146 row_shl:15 row_mask:0xf bank_mask:0xf
	v_fmac_f32_dpp v167, v121, v147 row_shl:15 row_mask:0xf bank_mask:0xf
	v_fmac_f32_dpp v168, v122, v148 row_shl:15 row_mask:0xf bank_mask:0xf
	v_fmac_f32_dpp v169, v123, v149 row_shl:15 row_mask:0xf bank_mask:0xf
	v_fmac_f32_dpp v162, v124, v130 row_shl:14 row_mask:0xf bank_mask:0xf
	v_fmac_f32_dpp v163, v125, v131 row_shl:14 row_mask:0xf bank_mask:0xf
	v_fmac_f32_dpp v164, v126, v132 row_shl:14 row_mask:0xf bank_mask:0xf
	v_fmac_f32_dpp v165, v127, v133 row_shl:14 row_mask:0xf bank_mask:0xf
	v_fmac_f32_dpp v166, v120, v142 row_shl:14 row_mask:0xf bank_mask:0xf
	v_fmac_f32_dpp v167, v121, v143 row_shl:14 row_mask:0xf bank_mask:0xf
	v_fmac_f32_dpp v168, v122, v144 row_shl:14 row_mask:0xf bank_mask:0xf
	v_fmac_f32_dpp v169, v123, v145 row_shl:14 row_mask:0xf bank_mask:0xf
	v_mul_f32_e32 v230, 0xbfb8aa3b, v162
	v_mul_f32_e32 v231, 0xbfb8aa3b, v163
	v_mul_f32_e32 v232, 0xbfb8aa3b, v164
	v_mul_f32_e32 v233, 0xbfb8aa3b, v165
	v_exp_f32_e32 v230, v230
	v_exp_f32_e32 v231, v231
	v_exp_f32_e32 v232, v232
	v_exp_f32_e32 v233, v233
	v_add_f32_e32 v230, 1.0, v230
	v_add_f32_e32 v231, 1.0, v231
	v_add_f32_e32 v232, 1.0, v232
	v_add_f32_e32 v233, 1.0, v233
	v_rcp_f32_e32 v230, v230
	v_rcp_f32_e32 v231, v231
	v_rcp_f32_e32 v232, v232
	v_rcp_f32_e32 v233, v233
	v_mul_f32_e32 v230, v162, v230
	v_mul_f32_e32 v231, v163, v231
	v_mul_f32_e32 v232, v164, v232
	v_mul_f32_e32 v233, v165, v233
	v_mul_f32_e32 v230, v230, v166
	v_mul_f32_e32 v231, v231, v167
	v_mul_f32_e32 v232, v232, v168
	v_mul_f32_e32 v233, v233, v169
	v_cvt_pk_bf16_f32 v226, v230, v231
	v_cvt_pk_bf16_f32 v227, v232, v233
	v_pk_mul_f32 v[108:109], v[108:109], v[218:219] op_sel_hi:[1,0]
	v_pk_mul_f32 v[110:111], v[110:111], v[218:219] op_sel_hi:[1,0]
	v_pk_mul_f32 v[104:105], v[104:105], v[218:219] op_sel_hi:[1,0]
	v_pk_mul_f32 v[106:107], v[106:107], v[218:219] op_sel_hi:[1,0]
	v_pk_mul_f32 v[162:163], v[108:109], v[138:139]
	v_pk_mul_f32 v[164:165], v[110:111], v[140:141]
	v_pk_mul_f32 v[166:167], v[104:105], v[150:151]
	v_pk_mul_f32 v[168:169], v[106:107], v[152:153]
	v_fmac_f32_dpp v162, v108, v134 row_shr:1 row_mask:0xf bank_mask:0xf
	v_fmac_f32_dpp v163, v109, v135 row_shr:1 row_mask:0xf bank_mask:0xf
	v_fmac_f32_dpp v164, v110, v136 row_shr:1 row_mask:0xf bank_mask:0xf
	v_fmac_f32_dpp v165, v111, v137 row_shr:1 row_mask:0xf bank_mask:0xf
	v_fmac_f32_dpp v166, v104, v146 row_shr:1 row_mask:0xf bank_mask:0xf
	v_fmac_f32_dpp v167, v105, v147 row_shr:1 row_mask:0xf bank_mask:0xf
	v_fmac_f32_dpp v168, v106, v148 row_shr:1 row_mask:0xf bank_mask:0xf
	v_fmac_f32_dpp v169, v107, v149 row_shr:1 row_mask:0xf bank_mask:0xf
	v_fmac_f32_dpp v162, v108, v130 row_shr:2 row_mask:0xf bank_mask:0xf
	v_fmac_f32_dpp v163, v109, v131 row_shr:2 row_mask:0xf bank_mask:0xf
	v_fmac_f32_dpp v164, v110, v132 row_shr:2 row_mask:0xf bank_mask:0xf
	v_fmac_f32_dpp v165, v111, v133 row_shr:2 row_mask:0xf bank_mask:0xf
	v_fmac_f32_dpp v166, v104, v142 row_shr:2 row_mask:0xf bank_mask:0xf
	v_fmac_f32_dpp v167, v105, v143 row_shr:2 row_mask:0xf bank_mask:0xf
	v_fmac_f32_dpp v168, v106, v144 row_shr:2 row_mask:0xf bank_mask:0xf
	v_fmac_f32_dpp v169, v107, v145 row_shr:2 row_mask:0xf bank_mask:0xf
	v_fmac_f32_dpp v162, v116, v134 row_shl:15 row_mask:0xf bank_mask:0xf
	v_fmac_f32_dpp v163, v117, v135 row_shl:15 row_mask:0xf bank_mask:0xf
	v_fmac_f32_dpp v164, v118, v136 row_shl:15 row_mask:0xf bank_mask:0xf
	v_fmac_f32_dpp v165, v119, v137 row_shl:15 row_mask:0xf bank_mask:0xf
	v_fmac_f32_dpp v166, v112, v146 row_shl:15 row_mask:0xf bank_mask:0xf
	v_fmac_f32_dpp v167, v113, v147 row_shl:15 row_mask:0xf bank_mask:0xf
	v_fmac_f32_dpp v168, v114, v148 row_shl:15 row_mask:0xf bank_mask:0xf
; __device__ __forceinline__ unsigned cvt_pk_bf16(float lo, float hi) { unsigned r; asm volatile("v_cvt_pk_bf16_f32 %0, %1, %2" : "=v"(r) : "v"(lo), "v"(hi)); return r; }
;     static __device__ __forceinline__ float dpp_shr1(float old, float src) { return __builtin_bit_cast(float, __builtin_amdgcn_update_dpp(__builtin_bit_cast(int, old), __builtin_bit_cast(int, src), 0x111, 0xf, 0xf, false)); }
;     static __device__ __forceinline__ float dpp_shr2(float old, float src) { return __builtin_bit_cast(float, __builtin_amdgcn_update_dpp(__builtin_bit_cast(int, old), __builtin_bit_cast(int, src), 0x112, 0xf, 0xf, false)); }
;     static __device__ __forceinline__ float dpp_ror1(float src) { return __builtin_bit_cast(float, __builtin_amdgcn_update_dpp(0, __builtin_bit_cast(int, src), 0x121, 0xf, 0xf, true)); }
;     static __device__ __forceinline__ float dpp_ror2(float src) { return __builtin_bit_cast(float, __builtin_amdgcn_update_dpp(0, __builtin_bit_cast(int, src), 0x122, 0xf, 0xf, true)); }
;     __device__ __forceinline__ void operator()(const f32x4 (&acc)[2][2][4][2], const Unit& u, int wr, int wc, int fr, int fq) const {
;     ...
;                 for (int j = 0; j < 3; ++j) w[bj][j] = *(const f32x4*)(cw + j * 11264 + bj * 5632 + u.pn * 128 + cidx + 4 * n);
;     ...
;                 for (int m = 0; m < 4; ++m) {
;                     f32x4 uu[2];
; #pragma unroll
;                     for (int bj = 0; bj < 2; ++bj) { const f32x4 cur = acc[ai][bj][m][n] * rs[ai][m];
; #pragma unroll
;                         for (int q = 0; q < 4; ++q) { const float p1 = dpp_shr1(o1[bj][q], cur[q]), p2 = dpp_shr2(o2[bj][q], cur[q]);
;                             uu[bj][q] = w[bj][0][q] * p2 + w[bj][1][q] * p1 + w[bj][2][q] * cur[q];
;                             o1[bj][q] = dpp_ror1(cur[q]); o2[bj][q] = dpp_ror2(cur[q]); } }
;                     u32x2v o;
;                     { const float a0 = uu[0][0] * __builtin_amdgcn_rcpf(1.f + __expf(-uu[0][0])) * uu[1][0], a1 = uu[0][1] * __builtin_amdgcn_rcpf(1.f + __expf(-uu[0][1])) * uu[1][1];
;                       const float a2 = uu[0][2] * __builtin_amdgcn_rcpf(1.f + __expf(-uu[0][2])) * uu[1][2], a3 = uu[0][3] * __builtin_amdgcn_rcpf(1.f + __expf(-uu[0][3])) * uu[1][3];
;                       o.x = cvt_pk_bf16(a0, a1); o.y = cvt_pk_bf16(a2, a3); }
	v_fmac_f32_dpp v169, v115, v149 row_shl:15 row_mask:0xf bank_mask:0xf
	v_fmac_f32_dpp v162, v116, v130 row_shl:14 row_mask:0xf bank_mask:0xf
	v_fmac_f32_dpp v163, v117, v131 row_shl:14 row_mask:0xf bank_mask:0xf
	v_fmac_f32_dpp v164, v118, v132 row_shl:14 row_mask:0xf bank_mask:0xf
	v_fmac_f32_dpp v165, v119, v133 row_shl:14 row_mask:0xf bank_mask:0xf
	v_fmac_f32_dpp v166, v112, v142 row_shl:14 row_mask:0xf bank_mask:0xf
	v_fmac_f32_dpp v167, v113, v143 row_shl:14 row_mask:0xf bank_mask:0xf
	v_fmac_f32_dpp v168, v114, v144 row_shl:14 row_mask:0xf bank_mask:0xf
	v_fmac_f32_dpp v169, v115, v145 row_shl:14 row_mask:0xf bank_mask:0xf
	v_mul_f32_e32 v230, 0xbfb8aa3b, v162
	v_mul_f32_e32 v231, 0xbfb8aa3b, v163
	v_mul_f32_e32 v232, 0xbfb8aa3b, v164
	v_mul_f32_e32 v233, 0xbfb8aa3b, v165
	v_exp_f32_e32 v230, v230
	v_exp_f32_e32 v231, v231
	v_exp_f32_e32 v232, v232
	v_exp_f32_e32 v233, v233
	v_add_f32_e32 v230, 1.0, v230
	v_add_f32_e32 v231, 1.0, v231
	v_add_f32_e32 v232, 1.0, v232
	v_add_f32_e32 v233, 1.0, v233
	v_rcp_f32_e32 v230, v230
	v_rcp_f32_e32 v231, v231
	v_rcp_f32_e32 v232, v232
	v_rcp_f32_e32 v233, v233
	v_mul_f32_e32 v230, v162, v230
	v_mul_f32_e32 v231, v163, v231
	v_mul_f32_e32 v232, v164, v232
	v_mul_f32_e32 v233, v165, v233
	v_mul_f32_e32 v230, v230, v166
	v_mul_f32_e32 v231, v231, v167
	v_mul_f32_e32 v232, v232, v168
	v_mul_f32_e32 v233, v233, v169
	v_cvt_pk_bf16_f32 v216, v230, v231
	v_cvt_pk_bf16_f32 v217, v232, v233
	v_pk_mul_f32 v[100:101], v[100:101], v[194:195] op_sel_hi:[1,0]
	v_pk_mul_f32 v[102:103], v[102:103], v[194:195] op_sel_hi:[1,0]
	v_pk_mul_f32 v[96:97], v[96:97], v[194:195] op_sel_hi:[1,0]
	v_pk_mul_f32 v[98:99], v[98:99], v[194:195] op_sel_hi:[1,0]
	v_pk_mul_f32 v[162:163], v[100:101], v[138:139]
	v_pk_mul_f32 v[164:165], v[102:103], v[140:141]
	v_pk_mul_f32 v[166:167], v[96:97], v[150:151]
	v_pk_mul_f32 v[168:169], v[98:99], v[152:153]
	v_fmac_f32_dpp v162, v100, v134 row_shr:1 row_mask:0xf bank_mask:0xf
	v_fmac_f32_dpp v163, v101, v135 row_shr:1 row_mask:0xf bank_mask:0xf
	v_fmac_f32_dpp v164, v102, v136 row_shr:1 row_mask:0xf bank_mask:0xf
	v_fmac_f32_dpp v165, v103, v137 row_shr:1 row_mask:0xf bank_mask:0xf
	v_fmac_f32_dpp v166, v96, v146 row_shr:1 row_mask:0xf bank_mask:0xf
	v_fmac_f32_dpp v167, v97, v147 row_shr:1 row_mask:0xf bank_mask:0xf
	v_fmac_f32_dpp v168, v98, v148 row_shr:1 row_mask:0xf bank_mask:0xf
	v_fmac_f32_dpp v169, v99, v149 row_shr:1 row_mask:0xf bank_mask:0xf
	v_fmac_f32_dpp v162, v100, v130 row_shr:2 row_mask:0xf bank_mask:0xf
	v_fmac_f32_dpp v163, v101, v131 row_shr:2 row_mask:0xf bank_mask:0xf
	v_fmac_f32_dpp v164, v102, v132 row_shr:2 row_mask:0xf bank_mask:0xf
	v_fmac_f32_dpp v165, v103, v133 row_shr:2 row_mask:0xf bank_mask:0xf
	v_fmac_f32_dpp v166, v96, v142 row_shr:2 row_mask:0xf bank_mask:0xf
	v_fmac_f32_dpp v167, v97, v143 row_shr:2 row_mask:0xf bank_mask:0xf
	v_fmac_f32_dpp v168, v98, v144 row_shr:2 row_mask:0xf bank_mask:0xf
	v_fmac_f32_dpp v169, v99, v145 row_shr:2 row_mask:0xf bank_mask:0xf
	v_fmac_f32_dpp v162, v108, v134 row_shl:15 row_mask:0xf bank_mask:0xf
	v_fmac_f32_dpp v163, v109, v135 row_shl:15 row_mask:0xf bank_mask:0xf
	v_fmac_f32_dpp v164, v110, v136 row_shl:15 row_mask:0xf bank_mask:0xf
	v_fmac_f32_dpp v165, v111, v137 row_shl:15 row_mask:0xf bank_mask:0xf
	v_fmac_f32_dpp v166, v104, v146 row_shl:15 row_mask:0xf bank_mask:0xf
	v_fmac_f32_dpp v167, v105, v147 row_shl:15 row_mask:0xf bank_mask:0xf
	v_fmac_f32_dpp v168, v106, v148 row_shl:15 row_mask:0xf bank_mask:0xf
	v_fmac_f32_dpp v169, v107, v149 row_shl:15 row_mask:0xf bank_mask:0xf
	v_fmac_f32_dpp v162, v108, v130 row_shl:14 row_mask:0xf bank_mask:0xf
	v_fmac_f32_dpp v163, v109, v131 row_shl:14 row_mask:0xf bank_mask:0xf
	v_fmac_f32_dpp v164, v110, v132 row_shl:14 row_mask:0xf bank_mask:0xf
	v_fmac_f32_dpp v165, v111, v133 row_shl:14 row_mask:0xf bank_mask:0xf
	v_fmac_f32_dpp v166, v104, v142 row_shl:14 row_mask:0xf bank_mask:0xf
	v_fmac_f32_dpp v167, v105, v143 row_shl:14 row_mask:0xf bank_mask:0xf
	v_fmac_f32_dpp v168, v106, v144 row_shl:14 row_mask:0xf bank_mask:0xf
	v_fmac_f32_dpp v169, v107, v145 row_shl:14 row_mask:0xf bank_mask:0xf
	v_mul_f32_e32 v230, 0xbfb8aa3b, v162
	v_mul_f32_e32 v231, 0xbfb8aa3b, v163
	v_mul_f32_e32 v232, 0xbfb8aa3b, v164
	v_mul_f32_e32 v233, 0xbfb8aa3b, v165
	v_exp_f32_e32 v230, v230
	v_exp_f32_e32 v231, v231
	v_exp_f32_e32 v232, v232
	v_exp_f32_e32 v233, v233
	v_add_f32_e32 v230, 1.0, v230
	v_add_f32_e32 v231, 1.0, v231
	v_add_f32_e32 v232, 1.0, v232
	v_add_f32_e32 v233, 1.0, v233
	v_rcp_f32_e32 v230, v230
	v_rcp_f32_e32 v231, v231
	v_rcp_f32_e32 v232, v232
	v_rcp_f32_e32 v233, v233
	v_mul_f32_e32 v230, v162, v230
	v_mul_f32_e32 v231, v163, v231
	v_mul_f32_e32 v232, v164, v232
	v_mul_f32_e32 v233, v165, v233
	v_mul_f32_e32 v230, v230, v166
	v_mul_f32_e32 v231, v231, v167
	v_mul_f32_e32 v232, v232, v168
	v_mul_f32_e32 v233, v233, v169
	v_cvt_pk_bf16_f32 v220, v230, v231
	v_cvt_pk_bf16_f32 v221, v232, v233
	global_load_dwordx4 v[96:99], v[222:223], off offset:16
	s_mov_b32 s8, 0xb010
	v_lshl_add_u64 v[234:235], v[222:223], 0, s[8:9]
	global_load_dwordx4 v[100:103], v[234:235], off
	s_mov_b32 s8, 0x16010
	v_lshl_add_u64 v[234:235], v[222:223], 0, s[8:9]
	global_load_dwordx4 v[104:107], v[234:235], off
	s_mov_b32 s8, 0x5810
	v_lshl_add_u64 v[234:235], v[222:223], 0, s[8:9]
	global_load_dwordx4 v[108:111], v[234:235], off
	s_mov_b32 s8, 0x10810
	v_lshl_add_u64 v[234:235], v[222:223], 0, s[8:9]
	global_load_dwordx4 v[112:115], v[234:235], off
	s_mov_b32 s8, 0x1b810
	v_lshl_add_u64 v[234:235], v[222:223], 0, s[8:9]
	global_load_dwordx4 v[116:119], v[234:235], off
	s_waitcnt lgkmcnt(0)
; #define PG8_LAS __attribute__((address_space(3)))
; __device__ __forceinline__ unsigned cvt_pk_bf16(float lo, float hi) { unsigned r; asm volatile("v_cvt_pk_bf16_f32 %0, %1, %2" : "=v"(r) : "v"(lo), "v"(hi)); return r; }
;     static __device__ __forceinline__ float dpp_shr1(float old, float src) { return __builtin_bit_cast(float, __builtin_amdgcn_update_dpp(__builtin_bit_cast(int, old), __builtin_bit_cast(int, src), 0x111, 0xf, 0xf, false)); }
;     __device__ __forceinline__ void operator()(const f32x4 (&acc)[2][2][4][2], const Unit& u, int wr, int wc, int fr, int fq) const {
;     ...
;             for (int ai = 0; ai < 2; ++ai) {
;                 const int gi = ai * 2 + wr;
;                 f32x4 o1[2], o2[2];
; #pragma unroll
;                 for (int bj = 0; bj < 2; ++bj) {
;                     o1[bj] = (f32x4){0.f, 0.f, 0.f, 0.f}; o2[bj] = o1[bj];
;                     if (gi > 0) { o1[bj] = *(const PG8_LAS f32x4*)(xch + (((((gi - 1) * 2 + 1) * 2 + bj) * 128) + cidx + 4 * n) * 4);
;                                   o2[bj] = *(const PG8_LAS f32x4*)(xch + (((((gi - 1) * 2 + (fr == 0 ? 0 : 1)) * 2 + bj) * 128) + cidx + 4 * n) * 4); }
;                 }
; #pragma unroll
;                 for (int m = 0; m < 4; ++m) {
;                     f32x4 uu[2];
; #pragma unroll
;                     for (int bj = 0; bj < 2; ++bj) { const f32x4 cur = acc[ai][bj][m][n] * rs[ai][m];
; #pragma unroll
;                         for (int q = 0; q < 4; ++q) { const float p1 = dpp_shr1(o1[bj][q], cur[q]), p2 = dpp_shr2(o2[bj][q], cur[q]);
;                             uu[bj][q] = w[bj][0][q] * p2 + w[bj][1][q] * p1 + w[bj][2][q] * cur[q];
;                             o1[bj][q] = dpp_ror1(cur[q]); o2[bj][q] = dpp_ror2(cur[q]); } }
;                     u32x2v o;
;                     { const float a0 = uu[0][0] * __builtin_amdgcn_rcpf(1.f + __expf(-uu[0][0])) * uu[1][0], a1 = uu[0][1] * __builtin_amdgcn_rcpf(1.f + __expf(-uu[0][1])) * uu[1][1];
;                       const float a2 = uu[0][2] * __builtin_amdgcn_rcpf(1.f + __expf(-uu[0][2])) * uu[1][2], a3 = uu[0][3] * __builtin_amdgcn_rcpf(1.f + __expf(-uu[0][3])) * uu[1][3];
;                       o.x = cvt_pk_bf16(a0, a1); o.y = cvt_pk_bf16(a2, a3); }
	v_pk_mul_f32 v[92:93], v[92:93], v[198:199] op_sel_hi:[1,0]
	v_pk_mul_f32 v[94:95], v[94:95], v[198:199] op_sel_hi:[1,0]
	v_pk_mul_f32 v[88:89], v[88:89], v[198:199] op_sel_hi:[1,0]
	v_pk_mul_f32 v[90:91], v[90:91], v[198:199] op_sel_hi:[1,0]
	v_pk_mul_f32 v[162:163], v[92:93], v[138:139]
	v_pk_mul_f32 v[164:165], v[94:95], v[140:141]
	v_pk_mul_f32 v[166:167], v[88:89], v[150:151]
	v_pk_mul_f32 v[168:169], v[90:91], v[152:153]
	v_fmac_f32_dpp v162, v92, v134 row_shr:1 row_mask:0xf bank_mask:0xf
	v_fmac_f32_dpp v163, v93, v135 row_shr:1 row_mask:0xf bank_mask:0xf
	v_fmac_f32_dpp v164, v94, v136 row_shr:1 row_mask:0xf bank_mask:0xf
	v_fmac_f32_dpp v165, v95, v137 row_shr:1 row_mask:0xf bank_mask:0xf
	v_fmac_f32_dpp v166, v88, v146 row_shr:1 row_mask:0xf bank_mask:0xf
	v_fmac_f32_dpp v167, v89, v147 row_shr:1 row_mask:0xf bank_mask:0xf
	v_fmac_f32_dpp v168, v90, v148 row_shr:1 row_mask:0xf bank_mask:0xf
	v_fmac_f32_dpp v169, v91, v149 row_shr:1 row_mask:0xf bank_mask:0xf
	v_fmac_f32_dpp v162, v92, v130 row_shr:2 row_mask:0xf bank_mask:0xf
	v_fmac_f32_dpp v163, v93, v131 row_shr:2 row_mask:0xf bank_mask:0xf
	v_fmac_f32_dpp v164, v94, v132 row_shr:2 row_mask:0xf bank_mask:0xf
	v_fmac_f32_dpp v165, v95, v133 row_shr:2 row_mask:0xf bank_mask:0xf
	v_fmac_f32_dpp v166, v88, v142 row_shr:2 row_mask:0xf bank_mask:0xf
	v_fmac_f32_dpp v167, v89, v143 row_shr:2 row_mask:0xf bank_mask:0xf
	v_fmac_f32_dpp v168, v90, v144 row_shr:2 row_mask:0xf bank_mask:0xf
	v_fmac_f32_dpp v169, v91, v145 row_shr:2 row_mask:0xf bank_mask:0xf
	v_fmac_f32_dpp v162, v154, v134 row_shl:15 row_mask:0xf bank_mask:0xf
	v_fmac_f32_dpp v163, v155, v135 row_shl:15 row_mask:0xf bank_mask:0xf
	v_fmac_f32_dpp v164, v156, v136 row_shl:15 row_mask:0xf bank_mask:0xf
	v_fmac_f32_dpp v165, v157, v137 row_shl:15 row_mask:0xf bank_mask:0xf
	v_fmac_f32_dpp v166, v158, v146 row_shl:15 row_mask:0xf bank_mask:0xf
	v_fmac_f32_dpp v167, v159, v147 row_shl:15 row_mask:0xf bank_mask:0xf
	v_fmac_f32_dpp v168, v160, v148 row_shl:15 row_mask:0xf bank_mask:0xf
	v_fmac_f32_dpp v169, v161, v149 row_shl:15 row_mask:0xf bank_mask:0xf
	v_fmac_f32_dpp v162, v154, v130 row_shl:14 row_mask:0xf bank_mask:0xf
	v_fmac_f32_dpp v163, v155, v131 row_shl:14 row_mask:0xf bank_mask:0xf
	v_fmac_f32_dpp v164, v156, v132 row_shl:14 row_mask:0xf bank_mask:0xf
	v_fmac_f32_dpp v165, v157, v133 row_shl:14 row_mask:0xf bank_mask:0xf
	v_fmac_f32_dpp v166, v158, v142 row_shl:14 row_mask:0xf bank_mask:0xf
	v_fmac_f32_dpp v167, v159, v143 row_shl:14 row_mask:0xf bank_mask:0xf
	v_fmac_f32_dpp v168, v160, v144 row_shl:14 row_mask:0xf bank_mask:0xf
	v_fmac_f32_dpp v169, v161, v145 row_shl:14 row_mask:0xf bank_mask:0xf
	v_mul_f32_e32 v230, 0xbfb8aa3b, v162
	v_mul_f32_e32 v231, 0xbfb8aa3b, v163
	v_mul_f32_e32 v232, 0xbfb8aa3b, v164
	v_mul_f32_e32 v233, 0xbfb8aa3b, v165
	v_exp_f32_e32 v230, v230
	v_exp_f32_e32 v231, v231
	v_exp_f32_e32 v232, v232
	v_exp_f32_e32 v233, v233
	v_add_f32_e32 v230, 1.0, v230
	v_add_f32_e32 v231, 1.0, v231
	v_add_f32_e32 v232, 1.0, v232
	v_add_f32_e32 v233, 1.0, v233
	v_rcp_f32_e32 v230, v230
	v_rcp_f32_e32 v231, v231
	v_rcp_f32_e32 v232, v232
	v_rcp_f32_e32 v233, v233
	v_mul_f32_e32 v230, v162, v230
	v_mul_f32_e32 v231, v163, v231
	v_mul_f32_e32 v232, v164, v232
	v_mul_f32_e32 v233, v165, v233
	v_mul_f32_e32 v230, v230, v166
	v_mul_f32_e32 v231, v231, v167
	v_mul_f32_e32 v232, v232, v168
	v_mul_f32_e32 v233, v233, v169
	v_cvt_pk_bf16_f32 v212, v230, v231
	v_cvt_pk_bf16_f32 v213, v232, v233
	s_cmp_eq_u32 s28, 0
	s_cbranch_scc1 .Lupc_zero_b2
	ds_read_b128 v[154:157], v197 offset:16
	ds_read_b128 v[158:161], v197 offset:528
	s_branch .Lupc_go_b2

; __device__ __forceinline__ unsigned cvt_pk_bf16(float lo, float hi) { unsigned r; asm volatile("v_cvt_pk_bf16_f32 %0, %1, %2" : "=v"(r) : "v"(lo), "v"(hi)); return r; }
;     static __device__ __forceinline__ float dpp_shr1(float old, float src) { return __builtin_bit_cast(float, __builtin_amdgcn_update_dpp(__builtin_bit_cast(int, old), __builtin_bit_cast(int, src), 0x111, 0xf, 0xf, false)); }
;     static __device__ __forceinline__ float dpp_shr2(float old, float src) { return __builtin_bit_cast(float, __builtin_amdgcn_update_dpp(__builtin_bit_cast(int, old), __builtin_bit_cast(int, src), 0x112, 0xf, 0xf, false)); }
;     static __device__ __forceinline__ float dpp_ror1(float src) { return __builtin_bit_cast(float, __builtin_amdgcn_update_dpp(0, __builtin_bit_cast(int, src), 0x121, 0xf, 0xf, true)); }
;     static __device__ __forceinline__ float dpp_ror2(float src) { return __builtin_bit_cast(float, __builtin_amdgcn_update_dpp(0, __builtin_bit_cast(int, src), 0x122, 0xf, 0xf, true)); }
;     __device__ __forceinline__ void operator()(const f32x4 (&acc)[2][2][4][2], const Unit& u, int wr, int wc, int fr, int fq) const {
;     ...
;                 for (int m = 0; m < 4; ++m) {
;                     f32x4 uu[2];
; #pragma unroll
;                     for (int bj = 0; bj < 2; ++bj) { const f32x4 cur = acc[ai][bj][m][n] * rs[ai][m];
; #pragma unroll
;                         for (int q = 0; q < 4; ++q) { const float p1 = dpp_shr1(o1[bj][q], cur[q]), p2 = dpp_shr2(o2[bj][q], cur[q]);
;                             uu[bj][q] = w[bj][0][q] * p2 + w[bj][1][q] * p1 + w[bj][2][q] * cur[q];
;                             o1[bj][q] = dpp_ror1(cur[q]); o2[bj][q] = dpp_ror2(cur[q]); } }
;                     u32x2v o;
;                     { const float a0 = uu[0][0] * __builtin_amdgcn_rcpf(1.f + __expf(-uu[0][0])) * uu[1][0], a1 = uu[0][1] * __builtin_amdgcn_rcpf(1.f + __expf(-uu[0][1])) * uu[1][1];
;                       const float a2 = uu[0][2] * __builtin_amdgcn_rcpf(1.f + __expf(-uu[0][2])) * uu[1][2], a3 = uu[0][3] * __builtin_amdgcn_rcpf(1.f + __expf(-uu[0][3])) * uu[1][3];
;                       o.x = cvt_pk_bf16(a0, a1); o.y = cvt_pk_bf16(a2, a3); }
.Lupc_go_b2:
	v_pk_mul_f32 v[84:85], v[84:85], v[202:203] op_sel_hi:[1,0]
	v_pk_mul_f32 v[86:87], v[86:87], v[202:203] op_sel_hi:[1,0]
	v_pk_mul_f32 v[80:81], v[80:81], v[202:203] op_sel_hi:[1,0]
	v_pk_mul_f32 v[82:83], v[82:83], v[202:203] op_sel_hi:[1,0]
	v_pk_mul_f32 v[162:163], v[84:85], v[138:139]
	v_pk_mul_f32 v[164:165], v[86:87], v[140:141]
	v_pk_mul_f32 v[166:167], v[80:81], v[150:151]
	v_pk_mul_f32 v[168:169], v[82:83], v[152:153]
	v_fmac_f32_dpp v162, v84, v134 row_shr:1 row_mask:0xf bank_mask:0xf
	v_fmac_f32_dpp v163, v85, v135 row_shr:1 row_mask:0xf bank_mask:0xf
	v_fmac_f32_dpp v164, v86, v136 row_shr:1 row_mask:0xf bank_mask:0xf
	v_fmac_f32_dpp v165, v87, v137 row_shr:1 row_mask:0xf bank_mask:0xf
	v_fmac_f32_dpp v166, v80, v146 row_shr:1 row_mask:0xf bank_mask:0xf
	v_fmac_f32_dpp v167, v81, v147 row_shr:1 row_mask:0xf bank_mask:0xf
	v_fmac_f32_dpp v168, v82, v148 row_shr:1 row_mask:0xf bank_mask:0xf
	v_fmac_f32_dpp v169, v83, v149 row_shr:1 row_mask:0xf bank_mask:0xf
	v_fmac_f32_dpp v162, v84, v130 row_shr:2 row_mask:0xf bank_mask:0xf
	v_fmac_f32_dpp v163, v85, v131 row_shr:2 row_mask:0xf bank_mask:0xf
	v_fmac_f32_dpp v164, v86, v132 row_shr:2 row_mask:0xf bank_mask:0xf
	v_fmac_f32_dpp v165, v87, v133 row_shr:2 row_mask:0xf bank_mask:0xf
	v_fmac_f32_dpp v166, v80, v142 row_shr:2 row_mask:0xf bank_mask:0xf
	v_fmac_f32_dpp v167, v81, v143 row_shr:2 row_mask:0xf bank_mask:0xf
	v_fmac_f32_dpp v168, v82, v144 row_shr:2 row_mask:0xf bank_mask:0xf
	v_fmac_f32_dpp v169, v83, v145 row_shr:2 row_mask:0xf bank_mask:0xf
	v_fmac_f32_dpp v162, v92, v134 row_shl:15 row_mask:0xf bank_mask:0xf
	v_fmac_f32_dpp v163, v93, v135 row_shl:15 row_mask:0xf bank_mask:0xf
	v_fmac_f32_dpp v164, v94, v136 row_shl:15 row_mask:0xf bank_mask:0xf
	v_fmac_f32_dpp v165, v95, v137 row_shl:15 row_mask:0xf bank_mask:0xf
	v_fmac_f32_dpp v166, v88, v146 row_shl:15 row_mask:0xf bank_mask:0xf
	v_fmac_f32_dpp v167, v89, v147 row_shl:15 row_mask:0xf bank_mask:0xf
	v_fmac_f32_dpp v168, v90, v148 row_shl:15 row_mask:0xf bank_mask:0xf
	v_fmac_f32_dpp v169, v91, v149 row_shl:15 row_mask:0xf bank_mask:0xf
	v_fmac_f32_dpp v162, v92, v130 row_shl:14 row_mask:0xf bank_mask:0xf
	v_fmac_f32_dpp v163, v93, v131 row_shl:14 row_mask:0xf bank_mask:0xf
	v_fmac_f32_dpp v164, v94, v132 row_shl:14 row_mask:0xf bank_mask:0xf
	v_fmac_f32_dpp v165, v95, v133 row_shl:14 row_mask:0xf bank_mask:0xf
	v_fmac_f32_dpp v166, v88, v142 row_shl:14 row_mask:0xf bank_mask:0xf
	v_fmac_f32_dpp v167, v89, v143 row_shl:14 row_mask:0xf bank_mask:0xf
	v_fmac_f32_dpp v168, v90, v144 row_shl:14 row_mask:0xf bank_mask:0xf
	v_fmac_f32_dpp v169, v91, v145 row_shl:14 row_mask:0xf bank_mask:0xf
	v_mul_f32_e32 v230, 0xbfb8aa3b, v162
	v_mul_f32_e32 v231, 0xbfb8aa3b, v163
	v_mul_f32_e32 v232, 0xbfb8aa3b, v164
	v_mul_f32_e32 v233, 0xbfb8aa3b, v165
	v_exp_f32_e32 v230, v230
	v_exp_f32_e32 v231, v231
	v_exp_f32_e32 v232, v232
	v_exp_f32_e32 v233, v233
	v_add_f32_e32 v230, 1.0, v230
	v_add_f32_e32 v231, 1.0, v231
	v_add_f32_e32 v232, 1.0, v232
	v_add_f32_e32 v233, 1.0, v233
	v_rcp_f32_e32 v230, v230
	v_rcp_f32_e32 v231, v231
	v_rcp_f32_e32 v232, v232
	v_rcp_f32_e32 v233, v233
	v_mul_f32_e32 v230, v162, v230
	v_mul_f32_e32 v231, v163, v231
	v_mul_f32_e32 v232, v164, v232
	v_mul_f32_e32 v233, v165, v233
	v_mul_f32_e32 v230, v230, v166
	v_mul_f32_e32 v231, v231, v167
	v_mul_f32_e32 v232, v232, v168
	v_mul_f32_e32 v233, v233, v169
	v_cvt_pk_bf16_f32 v208, v230, v231
	v_cvt_pk_bf16_f32 v209, v232, v233
	v_pk_mul_f32 v[76:77], v[76:77], v[204:205] op_sel_hi:[1,0]
	v_pk_mul_f32 v[78:79], v[78:79], v[204:205] op_sel_hi:[1,0]
	v_pk_mul_f32 v[72:73], v[72:73], v[204:205] op_sel_hi:[1,0]
	v_pk_mul_f32 v[74:75], v[74:75], v[204:205] op_sel_hi:[1,0]
	v_pk_mul_f32 v[162:163], v[76:77], v[138:139]
	v_pk_mul_f32 v[164:165], v[78:79], v[140:141]
	v_pk_mul_f32 v[166:167], v[72:73], v[150:151]
	v_pk_mul_f32 v[168:169], v[74:75], v[152:153]
	v_fmac_f32_dpp v162, v76, v134 row_shr:1 row_mask:0xf bank_mask:0xf
	v_fmac_f32_dpp v163, v77, v135 row_shr:1 row_mask:0xf bank_mask:0xf
	v_fmac_f32_dpp v164, v78, v136 row_shr:1 row_mask:0xf bank_mask:0xf
	v_fmac_f32_dpp v165, v79, v137 row_shr:1 row_mask:0xf bank_mask:0xf
	v_fmac_f32_dpp v166, v72, v146 row_shr:1 row_mask:0xf bank_mask:0xf
	v_fmac_f32_dpp v167, v73, v147 row_shr:1 row_mask:0xf bank_mask:0xf
	v_fmac_f32_dpp v168, v74, v148 row_shr:1 row_mask:0xf bank_mask:0xf
	v_fmac_f32_dpp v169, v75, v149 row_shr:1 row_mask:0xf bank_mask:0xf
	v_fmac_f32_dpp v162, v76, v130 row_shr:2 row_mask:0xf bank_mask:0xf
	v_fmac_f32_dpp v163, v77, v131 row_shr:2 row_mask:0xf bank_mask:0xf
	v_fmac_f32_dpp v164, v78, v132 row_shr:2 row_mask:0xf bank_mask:0xf
	v_fmac_f32_dpp v165, v79, v133 row_shr:2 row_mask:0xf bank_mask:0xf
	v_fmac_f32_dpp v166, v72, v142 row_shr:2 row_mask:0xf bank_mask:0xf
	v_fmac_f32_dpp v167, v73, v143 row_shr:2 row_mask:0xf bank_mask:0xf
	v_fmac_f32_dpp v168, v74, v144 row_shr:2 row_mask:0xf bank_mask:0xf
	v_fmac_f32_dpp v169, v75, v145 row_shr:2 row_mask:0xf bank_mask:0xf
	v_fmac_f32_dpp v162, v84, v134 row_shl:15 row_mask:0xf bank_mask:0xf
	v_fmac_f32_dpp v163, v85, v135 row_shl:15 row_mask:0xf bank_mask:0xf
	v_fmac_f32_dpp v164, v86, v136 row_shl:15 row_mask:0xf bank_mask:0xf
	v_fmac_f32_dpp v165, v87, v137 row_shl:15 row_mask:0xf bank_mask:0xf
	v_fmac_f32_dpp v166, v80, v146 row_shl:15 row_mask:0xf bank_mask:0xf
	v_fmac_f32_dpp v167, v81, v147 row_shl:15 row_mask:0xf bank_mask:0xf
	v_fmac_f32_dpp v168, v82, v148 row_shl:15 row_mask:0xf bank_mask:0xf
	v_fmac_f32_dpp v169, v83, v149 row_shl:15 row_mask:0xf bank_mask:0xf
	v_fmac_f32_dpp v162, v84, v130 row_shl:14 row_mask:0xf bank_mask:0xf
; __device__ __forceinline__ unsigned cvt_pk_bf16(float lo, float hi) { unsigned r; asm volatile("v_cvt_pk_bf16_f32 %0, %1, %2" : "=v"(r) : "v"(lo), "v"(hi)); return r; }
;     static __device__ __forceinline__ float dpp_shr1(float old, float src) { return __builtin_bit_cast(float, __builtin_amdgcn_update_dpp(__builtin_bit_cast(int, old), __builtin_bit_cast(int, src), 0x111, 0xf, 0xf, false)); }
;     static __device__ __forceinline__ float dpp_shr2(float old, float src) { return __builtin_bit_cast(float, __builtin_amdgcn_update_dpp(__builtin_bit_cast(int, old), __builtin_bit_cast(int, src), 0x112, 0xf, 0xf, false)); }
;     static __device__ __forceinline__ float dpp_ror1(float src) { return __builtin_bit_cast(float, __builtin_amdgcn_update_dpp(0, __builtin_bit_cast(int, src), 0x121, 0xf, 0xf, true)); }
;     static __device__ __forceinline__ float dpp_ror2(float src) { return __builtin_bit_cast(float, __builtin_amdgcn_update_dpp(0, __builtin_bit_cast(int, src), 0x122, 0xf, 0xf, true)); }
;     __device__ __forceinline__ void operator()(const f32x4 (&acc)[2][2][4][2], const Unit& u, int wr, int wc, int fr, int fq) const {
;     ...
;                 for (int m = 0; m < 4; ++m) {
;                     f32x4 uu[2];
; #pragma unroll
;                     for (int bj = 0; bj < 2; ++bj) { const f32x4 cur = acc[ai][bj][m][n] * rs[ai][m];
; #pragma unroll
;                         for (int q = 0; q < 4; ++q) { const float p1 = dpp_shr1(o1[bj][q], cur[q]), p2 = dpp_shr2(o2[bj][q], cur[q]);
;                             uu[bj][q] = w[bj][0][q] * p2 + w[bj][1][q] * p1 + w[bj][2][q] * cur[q];
;                             o1[bj][q] = dpp_ror1(cur[q]); o2[bj][q] = dpp_ror2(cur[q]); } }
;                     u32x2v o;
;                     { const float a0 = uu[0][0] * __builtin_amdgcn_rcpf(1.f + __expf(-uu[0][0])) * uu[1][0], a1 = uu[0][1] * __builtin_amdgcn_rcpf(1.f + __expf(-uu[0][1])) * uu[1][1];
;                       const float a2 = uu[0][2] * __builtin_amdgcn_rcpf(1.f + __expf(-uu[0][2])) * uu[1][2], a3 = uu[0][3] * __builtin_amdgcn_rcpf(1.f + __expf(-uu[0][3])) * uu[1][3];
;                       o.x = cvt_pk_bf16(a0, a1); o.y = cvt_pk_bf16(a2, a3); }
;                     *(u32x2v*)(ACT + (size_t)(row0 + ai * HALF + m * 16) * 5632 + u.pn * 128 + cidx + 4 * n) = o;
	v_fmac_f32_dpp v163, v85, v131 row_shl:14 row_mask:0xf bank_mask:0xf
	v_fmac_f32_dpp v164, v86, v132 row_shl:14 row_mask:0xf bank_mask:0xf
	v_fmac_f32_dpp v165, v87, v133 row_shl:14 row_mask:0xf bank_mask:0xf
	v_fmac_f32_dpp v166, v80, v142 row_shl:14 row_mask:0xf bank_mask:0xf
	v_fmac_f32_dpp v167, v81, v143 row_shl:14 row_mask:0xf bank_mask:0xf
	v_fmac_f32_dpp v168, v82, v144 row_shl:14 row_mask:0xf bank_mask:0xf
	v_fmac_f32_dpp v169, v83, v145 row_shl:14 row_mask:0xf bank_mask:0xf
	v_mul_f32_e32 v230, 0xbfb8aa3b, v162
	v_mul_f32_e32 v231, 0xbfb8aa3b, v163
	v_mul_f32_e32 v232, 0xbfb8aa3b, v164
	v_mul_f32_e32 v233, 0xbfb8aa3b, v165
	v_exp_f32_e32 v230, v230
	v_exp_f32_e32 v231, v231
	v_exp_f32_e32 v232, v232
	v_exp_f32_e32 v233, v233
	v_add_f32_e32 v230, 1.0, v230
	v_add_f32_e32 v231, 1.0, v231
	v_add_f32_e32 v232, 1.0, v232
	v_add_f32_e32 v233, 1.0, v233
	v_rcp_f32_e32 v230, v230
	v_rcp_f32_e32 v231, v231
	v_rcp_f32_e32 v232, v232
	v_rcp_f32_e32 v233, v233
	v_mul_f32_e32 v230, v162, v230
	v_mul_f32_e32 v231, v163, v231
	v_mul_f32_e32 v232, v164, v232
	v_mul_f32_e32 v233, v165, v233
	v_mul_f32_e32 v230, v230, v166
	v_mul_f32_e32 v231, v231, v167
	v_mul_f32_e32 v232, v232, v168
	v_mul_f32_e32 v233, v233, v169
	v_cvt_pk_bf16_f32 v200, v230, v231
	v_cvt_pk_bf16_f32 v201, v232, v233
	v_pk_mul_f32 v[68:69], v[68:69], v[196:197] op_sel_hi:[1,0]
	v_pk_mul_f32 v[70:71], v[70:71], v[196:197] op_sel_hi:[1,0]
	v_pk_mul_f32 v[64:65], v[64:65], v[196:197] op_sel_hi:[1,0]
	v_pk_mul_f32 v[66:67], v[66:67], v[196:197] op_sel_hi:[1,0]
	v_pk_mul_f32 v[162:163], v[68:69], v[138:139]
	v_pk_mul_f32 v[164:165], v[70:71], v[140:141]
	v_pk_mul_f32 v[166:167], v[64:65], v[150:151]
	v_pk_mul_f32 v[168:169], v[66:67], v[152:153]
	v_fmac_f32_dpp v162, v68, v134 row_shr:1 row_mask:0xf bank_mask:0xf
	v_fmac_f32_dpp v163, v69, v135 row_shr:1 row_mask:0xf bank_mask:0xf
	v_fmac_f32_dpp v164, v70, v136 row_shr:1 row_mask:0xf bank_mask:0xf
	v_fmac_f32_dpp v165, v71, v137 row_shr:1 row_mask:0xf bank_mask:0xf
	v_fmac_f32_dpp v166, v64, v146 row_shr:1 row_mask:0xf bank_mask:0xf
	v_fmac_f32_dpp v167, v65, v147 row_shr:1 row_mask:0xf bank_mask:0xf
	v_fmac_f32_dpp v168, v66, v148 row_shr:1 row_mask:0xf bank_mask:0xf
	v_fmac_f32_dpp v169, v67, v149 row_shr:1 row_mask:0xf bank_mask:0xf
	v_fmac_f32_dpp v162, v68, v130 row_shr:2 row_mask:0xf bank_mask:0xf
	v_fmac_f32_dpp v163, v69, v131 row_shr:2 row_mask:0xf bank_mask:0xf
	v_fmac_f32_dpp v164, v70, v132 row_shr:2 row_mask:0xf bank_mask:0xf
	v_fmac_f32_dpp v165, v71, v133 row_shr:2 row_mask:0xf bank_mask:0xf
	v_fmac_f32_dpp v166, v64, v142 row_shr:2 row_mask:0xf bank_mask:0xf
	v_fmac_f32_dpp v167, v65, v143 row_shr:2 row_mask:0xf bank_mask:0xf
	v_fmac_f32_dpp v168, v66, v144 row_shr:2 row_mask:0xf bank_mask:0xf
	v_fmac_f32_dpp v169, v67, v145 row_shr:2 row_mask:0xf bank_mask:0xf
	v_fmac_f32_dpp v162, v76, v134 row_shl:15 row_mask:0xf bank_mask:0xf
	v_fmac_f32_dpp v163, v77, v135 row_shl:15 row_mask:0xf bank_mask:0xf
	v_fmac_f32_dpp v164, v78, v136 row_shl:15 row_mask:0xf bank_mask:0xf
	v_fmac_f32_dpp v165, v79, v137 row_shl:15 row_mask:0xf bank_mask:0xf
	v_fmac_f32_dpp v166, v72, v146 row_shl:15 row_mask:0xf bank_mask:0xf
	v_fmac_f32_dpp v167, v73, v147 row_shl:15 row_mask:0xf bank_mask:0xf
	v_fmac_f32_dpp v168, v74, v148 row_shl:15 row_mask:0xf bank_mask:0xf
	v_fmac_f32_dpp v169, v75, v149 row_shl:15 row_mask:0xf bank_mask:0xf
	v_fmac_f32_dpp v162, v76, v130 row_shl:14 row_mask:0xf bank_mask:0xf
	v_fmac_f32_dpp v163, v77, v131 row_shl:14 row_mask:0xf bank_mask:0xf
	v_fmac_f32_dpp v164, v78, v132 row_shl:14 row_mask:0xf bank_mask:0xf
	v_fmac_f32_dpp v165, v79, v133 row_shl:14 row_mask:0xf bank_mask:0xf
	v_fmac_f32_dpp v166, v72, v142 row_shl:14 row_mask:0xf bank_mask:0xf
	v_fmac_f32_dpp v167, v73, v143 row_shl:14 row_mask:0xf bank_mask:0xf
	v_fmac_f32_dpp v168, v74, v144 row_shl:14 row_mask:0xf bank_mask:0xf
	v_fmac_f32_dpp v169, v75, v145 row_shl:14 row_mask:0xf bank_mask:0xf
	v_mul_f32_e32 v230, 0xbfb8aa3b, v162
	v_mul_f32_e32 v231, 0xbfb8aa3b, v163
	v_mul_f32_e32 v232, 0xbfb8aa3b, v164
	v_mul_f32_e32 v233, 0xbfb8aa3b, v165
	v_exp_f32_e32 v230, v230
	v_exp_f32_e32 v231, v231
	v_exp_f32_e32 v232, v232
	v_exp_f32_e32 v233, v233
	v_add_f32_e32 v230, 1.0, v230
	v_add_f32_e32 v231, 1.0, v231
	v_add_f32_e32 v232, 1.0, v232
	v_add_f32_e32 v233, 1.0, v233
	v_rcp_f32_e32 v230, v230
	v_rcp_f32_e32 v231, v231
	v_rcp_f32_e32 v232, v232
	v_rcp_f32_e32 v233, v233
	v_mul_f32_e32 v230, v162, v230
	v_mul_f32_e32 v231, v163, v231
	v_mul_f32_e32 v232, v164, v232
	v_mul_f32_e32 v233, v165, v233
	v_mul_f32_e32 v230, v230, v166
	v_mul_f32_e32 v231, v231, v167
	v_mul_f32_e32 v232, v232, v168
	v_mul_f32_e32 v233, v233, v169
	v_cvt_pk_bf16_f32 v248, v230, v231
	v_cvt_pk_bf16_f32 v249, v232, v233
	s_waitcnt vmcnt(0)
	s_waitcnt lgkmcnt(0)
; #define PG8_LAS __attribute__((address_space(3)))
; __device__ __forceinline__ unsigned cvt_pk_bf16(float lo, float hi) { unsigned r; asm volatile("v_cvt_pk_bf16_f32 %0, %1, %2" : "=v"(r) : "v"(lo), "v"(hi)); return r; }
;     static __device__ __forceinline__ float dpp_shr1(float old, float src) { return __builtin_bit_cast(float, __builtin_amdgcn_update_dpp(__builtin_bit_cast(int, old), __builtin_bit_cast(int, src), 0x111, 0xf, 0xf, false)); }
;     static __device__ __forceinline__ float dpp_ror1(float src) { return __builtin_bit_cast(float, __builtin_amdgcn_update_dpp(0, __builtin_bit_cast(int, src), 0x121, 0xf, 0xf, true)); }
;     __device__ __forceinline__ void operator()(const f32x4 (&acc)[2][2][4][2], const Unit& u, int wr, int wc, int fr, int fq) const {
;     ...
;                 for (int bj = 0; bj < 2; ++bj) {
;                     o1[bj] = (f32x4){0.f, 0.f, 0.f, 0.f}; o2[bj] = o1[bj];
;                     if (gi > 0) { o1[bj] = *(const PG8_LAS f32x4*)(xch + (((((gi - 1) * 2 + 1) * 2 + bj) * 128) + cidx + 4 * n) * 4);
;                                   o2[bj] = *(const PG8_LAS f32x4*)(xch + (((((gi - 1) * 2 + (fr == 0 ? 0 : 1)) * 2 + bj) * 128) + cidx + 4 * n) * 4); }
;                 }
; #pragma unroll
;                 for (int m = 0; m < 4; ++m) {
;                     f32x4 uu[2];
; #pragma unroll
;                     for (int bj = 0; bj < 2; ++bj) { const f32x4 cur = acc[ai][bj][m][n] * rs[ai][m];
; #pragma unroll
;                         for (int q = 0; q < 4; ++q) { const float p1 = dpp_shr1(o1[bj][q], cur[q]), p2 = dpp_shr2(o2[bj][q], cur[q]);
;                             uu[bj][q] = w[bj][0][q] * p2 + w[bj][1][q] * p1 + w[bj][2][q] * cur[q];
;                             o1[bj][q] = dpp_ror1(cur[q]); o2[bj][q] = dpp_ror2(cur[q]); } }
;                     u32x2v o;
;                     { const float a0 = uu[0][0] * __builtin_amdgcn_rcpf(1.f + __expf(-uu[0][0])) * uu[1][0], a1 = uu[0][1] * __builtin_amdgcn_rcpf(1.f + __expf(-uu[0][1])) * uu[1][1];
;                       const float a2 = uu[0][2] * __builtin_amdgcn_rcpf(1.f + __expf(-uu[0][2])) * uu[1][2], a3 = uu[0][3] * __builtin_amdgcn_rcpf(1.f + __expf(-uu[0][3])) * uu[1][3];
;                       o.x = cvt_pk_bf16(a0, a1); o.y = cvt_pk_bf16(a2, a3); }
;                     *(u32x2v*)(ACT + (size_t)(row0 + ai * HALF + m * 16) * 5632 + u.pn * 128 + cidx + 4 * n) = o;
	v_pk_mul_f32 v[60:61], v[60:61], v[210:211] op_sel_hi:[1,0]
	v_pk_mul_f32 v[62:63], v[62:63], v[210:211] op_sel_hi:[1,0]
	v_pk_mul_f32 v[56:57], v[56:57], v[210:211] op_sel_hi:[1,0]
	v_pk_mul_f32 v[58:59], v[58:59], v[210:211] op_sel_hi:[1,0]
	v_pk_mul_f32 v[162:163], v[60:61], v[104:105]
	v_pk_mul_f32 v[164:165], v[62:63], v[106:107]
	v_pk_mul_f32 v[166:167], v[56:57], v[116:117]
	v_pk_mul_f32 v[168:169], v[58:59], v[118:119]
	v_fmac_f32_dpp v162, v60, v100 row_shr:1 row_mask:0xf bank_mask:0xf
	v_fmac_f32_dpp v163, v61, v101 row_shr:1 row_mask:0xf bank_mask:0xf
	v_fmac_f32_dpp v164, v62, v102 row_shr:1 row_mask:0xf bank_mask:0xf
	v_fmac_f32_dpp v165, v63, v103 row_shr:1 row_mask:0xf bank_mask:0xf
	v_fmac_f32_dpp v166, v56, v112 row_shr:1 row_mask:0xf bank_mask:0xf
	v_fmac_f32_dpp v167, v57, v113 row_shr:1 row_mask:0xf bank_mask:0xf
	v_fmac_f32_dpp v168, v58, v114 row_shr:1 row_mask:0xf bank_mask:0xf
	v_fmac_f32_dpp v169, v59, v115 row_shr:1 row_mask:0xf bank_mask:0xf
	v_fmac_f32_dpp v162, v60, v96 row_shr:2 row_mask:0xf bank_mask:0xf
	v_fmac_f32_dpp v163, v61, v97 row_shr:2 row_mask:0xf bank_mask:0xf
	v_fmac_f32_dpp v164, v62, v98 row_shr:2 row_mask:0xf bank_mask:0xf
	v_fmac_f32_dpp v165, v63, v99 row_shr:2 row_mask:0xf bank_mask:0xf
	v_fmac_f32_dpp v166, v56, v108 row_shr:2 row_mask:0xf bank_mask:0xf
	v_fmac_f32_dpp v167, v57, v109 row_shr:2 row_mask:0xf bank_mask:0xf
	v_fmac_f32_dpp v168, v58, v110 row_shr:2 row_mask:0xf bank_mask:0xf
	v_fmac_f32_dpp v169, v59, v111 row_shr:2 row_mask:0xf bank_mask:0xf
	v_fmac_f32_dpp v162, v154, v100 row_shl:15 row_mask:0xf bank_mask:0xf
	v_fmac_f32_dpp v163, v155, v101 row_shl:15 row_mask:0xf bank_mask:0xf
	v_fmac_f32_dpp v164, v156, v102 row_shl:15 row_mask:0xf bank_mask:0xf
	v_fmac_f32_dpp v165, v157, v103 row_shl:15 row_mask:0xf bank_mask:0xf
	v_fmac_f32_dpp v166, v158, v112 row_shl:15 row_mask:0xf bank_mask:0xf
	v_fmac_f32_dpp v167, v159, v113 row_shl:15 row_mask:0xf bank_mask:0xf
	v_fmac_f32_dpp v168, v160, v114 row_shl:15 row_mask:0xf bank_mask:0xf
	v_fmac_f32_dpp v169, v161, v115 row_shl:15 row_mask:0xf bank_mask:0xf
	v_fmac_f32_dpp v162, v154, v96 row_shl:14 row_mask:0xf bank_mask:0xf
	v_fmac_f32_dpp v163, v155, v97 row_shl:14 row_mask:0xf bank_mask:0xf
	v_fmac_f32_dpp v164, v156, v98 row_shl:14 row_mask:0xf bank_mask:0xf
	v_fmac_f32_dpp v165, v157, v99 row_shl:14 row_mask:0xf bank_mask:0xf
	v_fmac_f32_dpp v166, v158, v108 row_shl:14 row_mask:0xf bank_mask:0xf
	v_fmac_f32_dpp v167, v159, v109 row_shl:14 row_mask:0xf bank_mask:0xf
	v_fmac_f32_dpp v168, v160, v110 row_shl:14 row_mask:0xf bank_mask:0xf
	v_fmac_f32_dpp v169, v161, v111 row_shl:14 row_mask:0xf bank_mask:0xf
	v_mul_f32_e32 v230, 0xbfb8aa3b, v162
	v_mul_f32_e32 v231, 0xbfb8aa3b, v163
	v_mul_f32_e32 v232, 0xbfb8aa3b, v164
	v_mul_f32_e32 v233, 0xbfb8aa3b, v165
	v_exp_f32_e32 v230, v230
	v_exp_f32_e32 v231, v231
	v_exp_f32_e32 v232, v232
	v_exp_f32_e32 v233, v233
	v_add_f32_e32 v230, 1.0, v230
	v_add_f32_e32 v231, 1.0, v231
	v_add_f32_e32 v232, 1.0, v232
	v_add_f32_e32 v233, 1.0, v233
	v_rcp_f32_e32 v230, v230
	v_rcp_f32_e32 v231, v231
	v_rcp_f32_e32 v232, v232
	v_rcp_f32_e32 v233, v233
	v_mul_f32_e32 v230, v162, v230
	v_mul_f32_e32 v231, v163, v231
	v_mul_f32_e32 v232, v164, v232
	v_mul_f32_e32 v233, v165, v233
	v_mul_f32_e32 v230, v230, v166
	v_mul_f32_e32 v231, v231, v167
	v_mul_f32_e32 v232, v232, v168
	v_mul_f32_e32 v233, v233, v169
	v_mov_b32_e32 v64, v224
	v_mov_b32_e32 v65, v225
	v_cvt_pk_bf16_f32 v66, v230, v231
	v_cvt_pk_bf16_f32 v67, v232, v233
	global_store_dwordx4 v[246:247], v[64:67], off
	ds_read_b128 v[154:157], v197 offset:4112
	ds_read_b128 v[158:161], v197 offset:4624
	v_pk_mul_f32 v[52:53], v[52:53], v[214:215] op_sel_hi:[1,0]
	v_pk_mul_f32 v[54:55], v[54:55], v[214:215] op_sel_hi:[1,0]
	v_pk_mul_f32 v[48:49], v[48:49], v[214:215] op_sel_hi:[1,0]
	v_pk_mul_f32 v[50:51], v[50:51], v[214:215] op_sel_hi:[1,0]
	v_pk_mul_f32 v[162:163], v[52:53], v[104:105]
	v_pk_mul_f32 v[164:165], v[54:55], v[106:107]
	v_pk_mul_f32 v[166:167], v[48:49], v[116:117]
	v_pk_mul_f32 v[168:169], v[50:51], v[118:119]
	v_fmac_f32_dpp v162, v52, v100 row_shr:1 row_mask:0xf bank_mask:0xf
	v_fmac_f32_dpp v163, v53, v101 row_shr:1 row_mask:0xf bank_mask:0xf
	v_fmac_f32_dpp v164, v54, v102 row_shr:1 row_mask:0xf bank_mask:0xf
	v_fmac_f32_dpp v165, v55, v103 row_shr:1 row_mask:0xf bank_mask:0xf
	v_fmac_f32_dpp v166, v48, v112 row_shr:1 row_mask:0xf bank_mask:0xf
	v_fmac_f32_dpp v167, v49, v113 row_shr:1 row_mask:0xf bank_mask:0xf
	v_fmac_f32_dpp v168, v50, v114 row_shr:1 row_mask:0xf bank_mask:0xf
	v_fmac_f32_dpp v169, v51, v115 row_shr:1 row_mask:0xf bank_mask:0xf
	v_fmac_f32_dpp v162, v52, v96 row_shr:2 row_mask:0xf bank_mask:0xf
	v_fmac_f32_dpp v163, v53, v97 row_shr:2 row_mask:0xf bank_mask:0xf
	v_fmac_f32_dpp v164, v54, v98 row_shr:2 row_mask:0xf bank_mask:0xf
	v_fmac_f32_dpp v165, v55, v99 row_shr:2 row_mask:0xf bank_mask:0xf
	v_fmac_f32_dpp v166, v48, v108 row_shr:2 row_mask:0xf bank_mask:0xf
	v_fmac_f32_dpp v167, v49, v109 row_shr:2 row_mask:0xf bank_mask:0xf
	v_fmac_f32_dpp v168, v50, v110 row_shr:2 row_mask:0xf bank_mask:0xf
	v_fmac_f32_dpp v169, v51, v111 row_shr:2 row_mask:0xf bank_mask:0xf
	v_fmac_f32_dpp v162, v60, v100 row_shl:15 row_mask:0xf bank_mask:0xf
	v_fmac_f32_dpp v163, v61, v101 row_shl:15 row_mask:0xf bank_mask:0xf
	v_fmac_f32_dpp v164, v62, v102 row_shl:15 row_mask:0xf bank_mask:0xf
	v_fmac_f32_dpp v165, v63, v103 row_shl:15 row_mask:0xf bank_mask:0xf
	v_fmac_f32_dpp v166, v56, v112 row_shl:15 row_mask:0xf bank_mask:0xf
	v_fmac_f32_dpp v167, v57, v113 row_shl:15 row_mask:0xf bank_mask:0xf
; __device__ __forceinline__ unsigned cvt_pk_bf16(float lo, float hi) { unsigned r; asm volatile("v_cvt_pk_bf16_f32 %0, %1, %2" : "=v"(r) : "v"(lo), "v"(hi)); return r; }
;     static __device__ __forceinline__ float dpp_shr1(float old, float src) { return __builtin_bit_cast(float, __builtin_amdgcn_update_dpp(__builtin_bit_cast(int, old), __builtin_bit_cast(int, src), 0x111, 0xf, 0xf, false)); }
;     static __device__ __forceinline__ float dpp_shr2(float old, float src) { return __builtin_bit_cast(float, __builtin_amdgcn_update_dpp(__builtin_bit_cast(int, old), __builtin_bit_cast(int, src), 0x112, 0xf, 0xf, false)); }
;     static __device__ __forceinline__ float dpp_ror1(float src) { return __builtin_bit_cast(float, __builtin_amdgcn_update_dpp(0, __builtin_bit_cast(int, src), 0x121, 0xf, 0xf, true)); }
;     static __device__ __forceinline__ float dpp_ror2(float src) { return __builtin_bit_cast(float, __builtin_amdgcn_update_dpp(0, __builtin_bit_cast(int, src), 0x122, 0xf, 0xf, true)); }
;     __device__ __forceinline__ void operator()(const f32x4 (&acc)[2][2][4][2], const Unit& u, int wr, int wc, int fr, int fq) const {
;     ...
;                 for (int m = 0; m < 4; ++m) {
;                     f32x4 uu[2];
; #pragma unroll
;                     for (int bj = 0; bj < 2; ++bj) { const f32x4 cur = acc[ai][bj][m][n] * rs[ai][m];
; #pragma unroll
;                         for (int q = 0; q < 4; ++q) { const float p1 = dpp_shr1(o1[bj][q], cur[q]), p2 = dpp_shr2(o2[bj][q], cur[q]);
;                             uu[bj][q] = w[bj][0][q] * p2 + w[bj][1][q] * p1 + w[bj][2][q] * cur[q];
;                             o1[bj][q] = dpp_ror1(cur[q]); o2[bj][q] = dpp_ror2(cur[q]); } }
;                     u32x2v o;
;                     { const float a0 = uu[0][0] * __builtin_amdgcn_rcpf(1.f + __expf(-uu[0][0])) * uu[1][0], a1 = uu[0][1] * __builtin_amdgcn_rcpf(1.f + __expf(-uu[0][1])) * uu[1][1];
;                       const float a2 = uu[0][2] * __builtin_amdgcn_rcpf(1.f + __expf(-uu[0][2])) * uu[1][2], a3 = uu[0][3] * __builtin_amdgcn_rcpf(1.f + __expf(-uu[0][3])) * uu[1][3];
;                       o.x = cvt_pk_bf16(a0, a1); o.y = cvt_pk_bf16(a2, a3); }
;                     *(u32x2v*)(ACT + (size_t)(row0 + ai * HALF + m * 16) * 5632 + u.pn * 128 + cidx + 4 * n) = o;
	v_fmac_f32_dpp v168, v58, v114 row_shl:15 row_mask:0xf bank_mask:0xf
	v_fmac_f32_dpp v169, v59, v115 row_shl:15 row_mask:0xf bank_mask:0xf
	v_fmac_f32_dpp v162, v60, v96 row_shl:14 row_mask:0xf bank_mask:0xf
	v_fmac_f32_dpp v163, v61, v97 row_shl:14 row_mask:0xf bank_mask:0xf
	v_fmac_f32_dpp v164, v62, v98 row_shl:14 row_mask:0xf bank_mask:0xf
	v_fmac_f32_dpp v165, v63, v99 row_shl:14 row_mask:0xf bank_mask:0xf
	v_fmac_f32_dpp v166, v56, v108 row_shl:14 row_mask:0xf bank_mask:0xf
	v_fmac_f32_dpp v167, v57, v109 row_shl:14 row_mask:0xf bank_mask:0xf
	v_fmac_f32_dpp v168, v58, v110 row_shl:14 row_mask:0xf bank_mask:0xf
	v_fmac_f32_dpp v169, v59, v111 row_shl:14 row_mask:0xf bank_mask:0xf
	v_mul_f32_e32 v230, 0xbfb8aa3b, v162
	v_mul_f32_e32 v231, 0xbfb8aa3b, v163
	v_mul_f32_e32 v232, 0xbfb8aa3b, v164
	v_mul_f32_e32 v233, 0xbfb8aa3b, v165
	v_exp_f32_e32 v230, v230
	v_exp_f32_e32 v231, v231
	v_exp_f32_e32 v232, v232
	v_exp_f32_e32 v233, v233
	v_add_f32_e32 v230, 1.0, v230
	v_add_f32_e32 v231, 1.0, v231
	v_add_f32_e32 v232, 1.0, v232
	v_add_f32_e32 v233, 1.0, v233
	v_rcp_f32_e32 v230, v230
	v_rcp_f32_e32 v231, v231
	v_rcp_f32_e32 v232, v232
	v_rcp_f32_e32 v233, v233
	v_mul_f32_e32 v230, v162, v230
	v_mul_f32_e32 v231, v163, v231
	v_mul_f32_e32 v232, v164, v232
	v_mul_f32_e32 v233, v165, v233
	v_mul_f32_e32 v230, v230, v166
	v_mul_f32_e32 v231, v231, v167
	v_mul_f32_e32 v232, v232, v168
	v_mul_f32_e32 v233, v233, v169
	v_mov_b32_e32 v68, v226
	v_mov_b32_e32 v69, v227
	v_cvt_pk_bf16_f32 v70, v230, v231
	v_cvt_pk_bf16_f32 v71, v232, v233
	s_mov_b32 s8, 0x2c000
	v_lshl_add_u64 v[234:235], v[246:247], 0, s[8:9]
	global_store_dwordx4 v[234:235], v[68:71], off
	v_pk_mul_f32 v[44:45], v[44:45], v[218:219] op_sel_hi:[1,0]
	v_pk_mul_f32 v[46:47], v[46:47], v[218:219] op_sel_hi:[1,0]
	v_pk_mul_f32 v[40:41], v[40:41], v[218:219] op_sel_hi:[1,0]
	v_pk_mul_f32 v[42:43], v[42:43], v[218:219] op_sel_hi:[1,0]
	v_pk_mul_f32 v[162:163], v[44:45], v[104:105]
	v_pk_mul_f32 v[164:165], v[46:47], v[106:107]
	v_pk_mul_f32 v[166:167], v[40:41], v[116:117]
	v_pk_mul_f32 v[168:169], v[42:43], v[118:119]
	v_fmac_f32_dpp v162, v44, v100 row_shr:1 row_mask:0xf bank_mask:0xf
	v_fmac_f32_dpp v163, v45, v101 row_shr:1 row_mask:0xf bank_mask:0xf
	v_fmac_f32_dpp v164, v46, v102 row_shr:1 row_mask:0xf bank_mask:0xf
	v_fmac_f32_dpp v165, v47, v103 row_shr:1 row_mask:0xf bank_mask:0xf
	v_fmac_f32_dpp v166, v40, v112 row_shr:1 row_mask:0xf bank_mask:0xf
	v_fmac_f32_dpp v167, v41, v113 row_shr:1 row_mask:0xf bank_mask:0xf
	v_fmac_f32_dpp v168, v42, v114 row_shr:1 row_mask:0xf bank_mask:0xf
	v_fmac_f32_dpp v169, v43, v115 row_shr:1 row_mask:0xf bank_mask:0xf
	v_fmac_f32_dpp v162, v44, v96 row_shr:2 row_mask:0xf bank_mask:0xf
	v_fmac_f32_dpp v163, v45, v97 row_shr:2 row_mask:0xf bank_mask:0xf
	v_fmac_f32_dpp v164, v46, v98 row_shr:2 row_mask:0xf bank_mask:0xf
	v_fmac_f32_dpp v165, v47, v99 row_shr:2 row_mask:0xf bank_mask:0xf
	v_fmac_f32_dpp v166, v40, v108 row_shr:2 row_mask:0xf bank_mask:0xf
	v_fmac_f32_dpp v167, v41, v109 row_shr:2 row_mask:0xf bank_mask:0xf
	v_fmac_f32_dpp v168, v42, v110 row_shr:2 row_mask:0xf bank_mask:0xf
	v_fmac_f32_dpp v169, v43, v111 row_shr:2 row_mask:0xf bank_mask:0xf
	v_fmac_f32_dpp v162, v52, v100 row_shl:15 row_mask:0xf bank_mask:0xf
	v_fmac_f32_dpp v163, v53, v101 row_shl:15 row_mask:0xf bank_mask:0xf
	v_fmac_f32_dpp v164, v54, v102 row_shl:15 row_mask:0xf bank_mask:0xf
	v_fmac_f32_dpp v165, v55, v103 row_shl:15 row_mask:0xf bank_mask:0xf
	v_fmac_f32_dpp v166, v48, v112 row_shl:15 row_mask:0xf bank_mask:0xf
	v_fmac_f32_dpp v167, v49, v113 row_shl:15 row_mask:0xf bank_mask:0xf
	v_fmac_f32_dpp v168, v50, v114 row_shl:15 row_mask:0xf bank_mask:0xf
	v_fmac_f32_dpp v169, v51, v115 row_shl:15 row_mask:0xf bank_mask:0xf
	v_fmac_f32_dpp v162, v52, v96 row_shl:14 row_mask:0xf bank_mask:0xf
	v_fmac_f32_dpp v163, v53, v97 row_shl:14 row_mask:0xf bank_mask:0xf
	v_fmac_f32_dpp v164, v54, v98 row_shl:14 row_mask:0xf bank_mask:0xf
	v_fmac_f32_dpp v165, v55, v99 row_shl:14 row_mask:0xf bank_mask:0xf
	v_fmac_f32_dpp v166, v48, v108 row_shl:14 row_mask:0xf bank_mask:0xf
	v_fmac_f32_dpp v167, v49, v109 row_shl:14 row_mask:0xf bank_mask:0xf
	v_fmac_f32_dpp v168, v50, v110 row_shl:14 row_mask:0xf bank_mask:0xf
	v_fmac_f32_dpp v169, v51, v111 row_shl:14 row_mask:0xf bank_mask:0xf
	v_mul_f32_e32 v230, 0xbfb8aa3b, v162
	v_mul_f32_e32 v231, 0xbfb8aa3b, v163
	v_mul_f32_e32 v232, 0xbfb8aa3b, v164
	v_mul_f32_e32 v233, 0xbfb8aa3b, v165
	v_exp_f32_e32 v230, v230
	v_exp_f32_e32 v231, v231
	v_exp_f32_e32 v232, v232
	v_exp_f32_e32 v233, v233
	v_add_f32_e32 v230, 1.0, v230
	v_add_f32_e32 v231, 1.0, v231
	v_add_f32_e32 v232, 1.0, v232
	v_add_f32_e32 v233, 1.0, v233
	v_rcp_f32_e32 v230, v230
	v_rcp_f32_e32 v231, v231
	v_rcp_f32_e32 v232, v232
	v_rcp_f32_e32 v233, v233
	v_mul_f32_e32 v230, v162, v230
	v_mul_f32_e32 v231, v163, v231
	v_mul_f32_e32 v232, v164, v232
	v_mul_f32_e32 v233, v165, v233
	v_mul_f32_e32 v230, v230, v166
	v_mul_f32_e32 v231, v231, v167
	v_mul_f32_e32 v232, v232, v168
	v_mul_f32_e32 v233, v233, v169
	v_mov_b32_e32 v72, v216
	v_mov_b32_e32 v73, v217
	v_cvt_pk_bf16_f32 v74, v230, v231
	v_cvt_pk_bf16_f32 v75, v232, v233
	s_mov_b32 s8, 0x58000
	v_lshl_add_u64 v[234:235], v[246:247], 0, s[8:9]
	global_store_dwordx4 v[234:235], v[72:75], off
	v_pk_mul_f32 v[36:37], v[36:37], v[194:195] op_sel_hi:[1,0]
	v_pk_mul_f32 v[38:39], v[38:39], v[194:195] op_sel_hi:[1,0]
	v_pk_mul_f32 v[32:33], v[32:33], v[194:195] op_sel_hi:[1,0]
	v_pk_mul_f32 v[34:35], v[34:35], v[194:195] op_sel_hi:[1,0]
	v_pk_mul_f32 v[162:163], v[36:37], v[104:105]
	v_pk_mul_f32 v[164:165], v[38:39], v[106:107]
; __device__ __forceinline__ unsigned cvt_pk_bf16(float lo, float hi) { unsigned r; asm volatile("v_cvt_pk_bf16_f32 %0, %1, %2" : "=v"(r) : "v"(lo), "v"(hi)); return r; }
;     static __device__ __forceinline__ float dpp_shr1(float old, float src) { return __builtin_bit_cast(float, __builtin_amdgcn_update_dpp(__builtin_bit_cast(int, old), __builtin_bit_cast(int, src), 0x111, 0xf, 0xf, false)); }
;     static __device__ __forceinline__ float dpp_shr2(float old, float src) { return __builtin_bit_cast(float, __builtin_amdgcn_update_dpp(__builtin_bit_cast(int, old), __builtin_bit_cast(int, src), 0x112, 0xf, 0xf, false)); }
;     static __device__ __forceinline__ float dpp_ror1(float src) { return __builtin_bit_cast(float, __builtin_amdgcn_update_dpp(0, __builtin_bit_cast(int, src), 0x121, 0xf, 0xf, true)); }
;     static __device__ __forceinline__ float dpp_ror2(float src) { return __builtin_bit_cast(float, __builtin_amdgcn_update_dpp(0, __builtin_bit_cast(int, src), 0x122, 0xf, 0xf, true)); }
;     __device__ __forceinline__ void operator()(const f32x4 (&acc)[2][2][4][2], const Unit& u, int wr, int wc, int fr, int fq) const {
;     ...
;                 for (int m = 0; m < 4; ++m) {
;                     f32x4 uu[2];
; #pragma unroll
;                     for (int bj = 0; bj < 2; ++bj) { const f32x4 cur = acc[ai][bj][m][n] * rs[ai][m];
; #pragma unroll
;                         for (int q = 0; q < 4; ++q) { const float p1 = dpp_shr1(o1[bj][q], cur[q]), p2 = dpp_shr2(o2[bj][q], cur[q]);
;                             uu[bj][q] = w[bj][0][q] * p2 + w[bj][1][q] * p1 + w[bj][2][q] * cur[q];
;                             o1[bj][q] = dpp_ror1(cur[q]); o2[bj][q] = dpp_ror2(cur[q]); } }
;                     u32x2v o;
;                     { const float a0 = uu[0][0] * __builtin_amdgcn_rcpf(1.f + __expf(-uu[0][0])) * uu[1][0], a1 = uu[0][1] * __builtin_amdgcn_rcpf(1.f + __expf(-uu[0][1])) * uu[1][1];
;                       const float a2 = uu[0][2] * __builtin_amdgcn_rcpf(1.f + __expf(-uu[0][2])) * uu[1][2], a3 = uu[0][3] * __builtin_amdgcn_rcpf(1.f + __expf(-uu[0][3])) * uu[1][3];
;                       o.x = cvt_pk_bf16(a0, a1); o.y = cvt_pk_bf16(a2, a3); }
;                     *(u32x2v*)(ACT + (size_t)(row0 + ai * HALF + m * 16) * 5632 + u.pn * 128 + cidx + 4 * n) = o;
	v_pk_mul_f32 v[166:167], v[32:33], v[116:117]
	v_pk_mul_f32 v[168:169], v[34:35], v[118:119]
	v_fmac_f32_dpp v162, v36, v100 row_shr:1 row_mask:0xf bank_mask:0xf
	v_fmac_f32_dpp v163, v37, v101 row_shr:1 row_mask:0xf bank_mask:0xf
	v_fmac_f32_dpp v164, v38, v102 row_shr:1 row_mask:0xf bank_mask:0xf
	v_fmac_f32_dpp v165, v39, v103 row_shr:1 row_mask:0xf bank_mask:0xf
	v_fmac_f32_dpp v166, v32, v112 row_shr:1 row_mask:0xf bank_mask:0xf
	v_fmac_f32_dpp v167, v33, v113 row_shr:1 row_mask:0xf bank_mask:0xf
	v_fmac_f32_dpp v168, v34, v114 row_shr:1 row_mask:0xf bank_mask:0xf
	v_fmac_f32_dpp v169, v35, v115 row_shr:1 row_mask:0xf bank_mask:0xf
	v_fmac_f32_dpp v162, v36, v96 row_shr:2 row_mask:0xf bank_mask:0xf
	v_fmac_f32_dpp v163, v37, v97 row_shr:2 row_mask:0xf bank_mask:0xf
	v_fmac_f32_dpp v164, v38, v98 row_shr:2 row_mask:0xf bank_mask:0xf
	v_fmac_f32_dpp v165, v39, v99 row_shr:2 row_mask:0xf bank_mask:0xf
	v_fmac_f32_dpp v166, v32, v108 row_shr:2 row_mask:0xf bank_mask:0xf
	v_fmac_f32_dpp v167, v33, v109 row_shr:2 row_mask:0xf bank_mask:0xf
	v_fmac_f32_dpp v168, v34, v110 row_shr:2 row_mask:0xf bank_mask:0xf
	v_fmac_f32_dpp v169, v35, v111 row_shr:2 row_mask:0xf bank_mask:0xf
	v_fmac_f32_dpp v162, v44, v100 row_shl:15 row_mask:0xf bank_mask:0xf
	v_fmac_f32_dpp v163, v45, v101 row_shl:15 row_mask:0xf bank_mask:0xf
	v_fmac_f32_dpp v164, v46, v102 row_shl:15 row_mask:0xf bank_mask:0xf
	v_fmac_f32_dpp v165, v47, v103 row_shl:15 row_mask:0xf bank_mask:0xf
	v_fmac_f32_dpp v166, v40, v112 row_shl:15 row_mask:0xf bank_mask:0xf
	v_fmac_f32_dpp v167, v41, v113 row_shl:15 row_mask:0xf bank_mask:0xf
	v_fmac_f32_dpp v168, v42, v114 row_shl:15 row_mask:0xf bank_mask:0xf
	v_fmac_f32_dpp v169, v43, v115 row_shl:15 row_mask:0xf bank_mask:0xf
	v_fmac_f32_dpp v162, v44, v96 row_shl:14 row_mask:0xf bank_mask:0xf
	v_fmac_f32_dpp v163, v45, v97 row_shl:14 row_mask:0xf bank_mask:0xf
	v_fmac_f32_dpp v164, v46, v98 row_shl:14 row_mask:0xf bank_mask:0xf
	v_fmac_f32_dpp v165, v47, v99 row_shl:14 row_mask:0xf bank_mask:0xf
	v_fmac_f32_dpp v166, v40, v108 row_shl:14 row_mask:0xf bank_mask:0xf
	v_fmac_f32_dpp v167, v41, v109 row_shl:14 row_mask:0xf bank_mask:0xf
	v_fmac_f32_dpp v168, v42, v110 row_shl:14 row_mask:0xf bank_mask:0xf
	v_fmac_f32_dpp v169, v43, v111 row_shl:14 row_mask:0xf bank_mask:0xf
	v_mul_f32_e32 v230, 0xbfb8aa3b, v162
	v_mul_f32_e32 v231, 0xbfb8aa3b, v163
	v_mul_f32_e32 v232, 0xbfb8aa3b, v164
	v_mul_f32_e32 v233, 0xbfb8aa3b, v165
	v_exp_f32_e32 v230, v230
	v_exp_f32_e32 v231, v231
	v_exp_f32_e32 v232, v232
	v_exp_f32_e32 v233, v233
	v_add_f32_e32 v230, 1.0, v230
	v_add_f32_e32 v231, 1.0, v231
	v_add_f32_e32 v232, 1.0, v232
	v_add_f32_e32 v233, 1.0, v233
	v_rcp_f32_e32 v230, v230
	v_rcp_f32_e32 v231, v231
	v_rcp_f32_e32 v232, v232
	v_rcp_f32_e32 v233, v233
	v_mul_f32_e32 v230, v162, v230
	v_mul_f32_e32 v231, v163, v231
	v_mul_f32_e32 v232, v164, v232
	v_mul_f32_e32 v233, v165, v233
	v_mul_f32_e32 v230, v230, v166
	v_mul_f32_e32 v231, v231, v167
	v_mul_f32_e32 v232, v232, v168
	v_mul_f32_e32 v233, v233, v169
	v_mov_b32_e32 v76, v220
	v_mov_b32_e32 v77, v221
	v_cvt_pk_bf16_f32 v78, v230, v231
	v_cvt_pk_bf16_f32 v79, v232, v233
	s_mov_b32 s8, 0x84000
	v_lshl_add_u64 v[234:235], v[246:247], 0, s[8:9]
	global_store_dwordx4 v[234:235], v[76:79], off
	s_waitcnt lgkmcnt(0)
	v_pk_mul_f32 v[28:29], v[28:29], v[198:199] op_sel_hi:[1,0]
	v_pk_mul_f32 v[30:31], v[30:31], v[198:199] op_sel_hi:[1,0]
	v_pk_mul_f32 v[24:25], v[24:25], v[198:199] op_sel_hi:[1,0]
	v_pk_mul_f32 v[26:27], v[26:27], v[198:199] op_sel_hi:[1,0]
	v_pk_mul_f32 v[162:163], v[28:29], v[104:105]
	v_pk_mul_f32 v[164:165], v[30:31], v[106:107]
	v_pk_mul_f32 v[166:167], v[24:25], v[116:117]
	v_pk_mul_f32 v[168:169], v[26:27], v[118:119]
	v_fmac_f32_dpp v162, v28, v100 row_shr:1 row_mask:0xf bank_mask:0xf
	v_fmac_f32_dpp v163, v29, v101 row_shr:1 row_mask:0xf bank_mask:0xf
	v_fmac_f32_dpp v164, v30, v102 row_shr:1 row_mask:0xf bank_mask:0xf
	v_fmac_f32_dpp v165, v31, v103 row_shr:1 row_mask:0xf bank_mask:0xf
	v_fmac_f32_dpp v166, v24, v112 row_shr:1 row_mask:0xf bank_mask:0xf
	v_fmac_f32_dpp v167, v25, v113 row_shr:1 row_mask:0xf bank_mask:0xf
	v_fmac_f32_dpp v168, v26, v114 row_shr:1 row_mask:0xf bank_mask:0xf
	v_fmac_f32_dpp v169, v27, v115 row_shr:1 row_mask:0xf bank_mask:0xf
	v_fmac_f32_dpp v162, v28, v96 row_shr:2 row_mask:0xf bank_mask:0xf
	v_fmac_f32_dpp v163, v29, v97 row_shr:2 row_mask:0xf bank_mask:0xf
	v_fmac_f32_dpp v164, v30, v98 row_shr:2 row_mask:0xf bank_mask:0xf
	v_fmac_f32_dpp v165, v31, v99 row_shr:2 row_mask:0xf bank_mask:0xf
	v_fmac_f32_dpp v166, v24, v108 row_shr:2 row_mask:0xf bank_mask:0xf
	v_fmac_f32_dpp v167, v25, v109 row_shr:2 row_mask:0xf bank_mask:0xf
	v_fmac_f32_dpp v168, v26, v110 row_shr:2 row_mask:0xf bank_mask:0xf
	v_fmac_f32_dpp v169, v27, v111 row_shr:2 row_mask:0xf bank_mask:0xf
	v_fmac_f32_dpp v162, v154, v100 row_shl:15 row_mask:0xf bank_mask:0xf
	v_fmac_f32_dpp v163, v155, v101 row_shl:15 row_mask:0xf bank_mask:0xf
	v_fmac_f32_dpp v164, v156, v102 row_shl:15 row_mask:0xf bank_mask:0xf
	v_fmac_f32_dpp v165, v157, v103 row_shl:15 row_mask:0xf bank_mask:0xf
	v_fmac_f32_dpp v166, v158, v112 row_shl:15 row_mask:0xf bank_mask:0xf
	v_fmac_f32_dpp v167, v159, v113 row_shl:15 row_mask:0xf bank_mask:0xf
	v_fmac_f32_dpp v168, v160, v114 row_shl:15 row_mask:0xf bank_mask:0xf
	v_fmac_f32_dpp v169, v161, v115 row_shl:15 row_mask:0xf bank_mask:0xf
	v_fmac_f32_dpp v162, v154, v96 row_shl:14 row_mask:0xf bank_mask:0xf
	v_fmac_f32_dpp v163, v155, v97 row_shl:14 row_mask:0xf bank_mask:0xf
	v_fmac_f32_dpp v164, v156, v98 row_shl:14 row_mask:0xf bank_mask:0xf
; __device__ __forceinline__ unsigned cvt_pk_bf16(float lo, float hi) { unsigned r; asm volatile("v_cvt_pk_bf16_f32 %0, %1, %2" : "=v"(r) : "v"(lo), "v"(hi)); return r; }
;     static __device__ __forceinline__ float dpp_shr1(float old, float src) { return __builtin_bit_cast(float, __builtin_amdgcn_update_dpp(__builtin_bit_cast(int, old), __builtin_bit_cast(int, src), 0x111, 0xf, 0xf, false)); }
;     static __device__ __forceinline__ float dpp_shr2(float old, float src) { return __builtin_bit_cast(float, __builtin_amdgcn_update_dpp(__builtin_bit_cast(int, old), __builtin_bit_cast(int, src), 0x112, 0xf, 0xf, false)); }
;     static __device__ __forceinline__ float dpp_ror1(float src) { return __builtin_bit_cast(float, __builtin_amdgcn_update_dpp(0, __builtin_bit_cast(int, src), 0x121, 0xf, 0xf, true)); }
;     static __device__ __forceinline__ float dpp_ror2(float src) { return __builtin_bit_cast(float, __builtin_amdgcn_update_dpp(0, __builtin_bit_cast(int, src), 0x122, 0xf, 0xf, true)); }
;     __device__ __forceinline__ void operator()(const f32x4 (&acc)[2][2][4][2], const Unit& u, int wr, int wc, int fr, int fq) const {
;     ...
;                 for (int m = 0; m < 4; ++m) {
;                     f32x4 uu[2];
; #pragma unroll
;                     for (int bj = 0; bj < 2; ++bj) { const f32x4 cur = acc[ai][bj][m][n] * rs[ai][m];
; #pragma unroll
;                         for (int q = 0; q < 4; ++q) { const float p1 = dpp_shr1(o1[bj][q], cur[q]), p2 = dpp_shr2(o2[bj][q], cur[q]);
;                             uu[bj][q] = w[bj][0][q] * p2 + w[bj][1][q] * p1 + w[bj][2][q] * cur[q];
;                             o1[bj][q] = dpp_ror1(cur[q]); o2[bj][q] = dpp_ror2(cur[q]); } }
;                     u32x2v o;
;                     { const float a0 = uu[0][0] * __builtin_amdgcn_rcpf(1.f + __expf(-uu[0][0])) * uu[1][0], a1 = uu[0][1] * __builtin_amdgcn_rcpf(1.f + __expf(-uu[0][1])) * uu[1][1];
;                       const float a2 = uu[0][2] * __builtin_amdgcn_rcpf(1.f + __expf(-uu[0][2])) * uu[1][2], a3 = uu[0][3] * __builtin_amdgcn_rcpf(1.f + __expf(-uu[0][3])) * uu[1][3];
;                       o.x = cvt_pk_bf16(a0, a1); o.y = cvt_pk_bf16(a2, a3); }
;                     *(u32x2v*)(ACT + (size_t)(row0 + ai * HALF + m * 16) * 5632 + u.pn * 128 + cidx + 4 * n) = o;
	v_fmac_f32_dpp v165, v157, v99 row_shl:14 row_mask:0xf bank_mask:0xf
	v_fmac_f32_dpp v166, v158, v108 row_shl:14 row_mask:0xf bank_mask:0xf
	v_fmac_f32_dpp v167, v159, v109 row_shl:14 row_mask:0xf bank_mask:0xf
	v_fmac_f32_dpp v168, v160, v110 row_shl:14 row_mask:0xf bank_mask:0xf
	v_fmac_f32_dpp v169, v161, v111 row_shl:14 row_mask:0xf bank_mask:0xf
	v_mul_f32_e32 v230, 0xbfb8aa3b, v162
	v_mul_f32_e32 v231, 0xbfb8aa3b, v163
	v_mul_f32_e32 v232, 0xbfb8aa3b, v164
	v_mul_f32_e32 v233, 0xbfb8aa3b, v165
	v_exp_f32_e32 v230, v230
	v_exp_f32_e32 v231, v231
	v_exp_f32_e32 v232, v232
	v_exp_f32_e32 v233, v233
	v_add_f32_e32 v230, 1.0, v230
	v_add_f32_e32 v231, 1.0, v231
	v_add_f32_e32 v232, 1.0, v232
	v_add_f32_e32 v233, 1.0, v233
	v_rcp_f32_e32 v230, v230
	v_rcp_f32_e32 v231, v231
	v_rcp_f32_e32 v232, v232
	v_rcp_f32_e32 v233, v233
	v_mul_f32_e32 v230, v162, v230
	v_mul_f32_e32 v231, v163, v231
	v_mul_f32_e32 v232, v164, v232
	v_mul_f32_e32 v233, v165, v233
	v_mul_f32_e32 v230, v230, v166
	v_mul_f32_e32 v231, v231, v167
	v_mul_f32_e32 v232, v232, v168
	v_mul_f32_e32 v233, v233, v169
	v_mov_b32_e32 v80, v212
	v_mov_b32_e32 v81, v213
	v_cvt_pk_bf16_f32 v82, v230, v231
	v_cvt_pk_bf16_f32 v83, v232, v233
	s_mov_b32 s8, 0x160000
	v_lshl_add_u64 v[234:235], v[246:247], 0, s[8:9]
	global_store_dwordx4 v[234:235], v[80:83], off
	v_pk_mul_f32 v[20:21], v[20:21], v[202:203] op_sel_hi:[1,0]
	v_pk_mul_f32 v[22:23], v[22:23], v[202:203] op_sel_hi:[1,0]
	v_pk_mul_f32 v[16:17], v[16:17], v[202:203] op_sel_hi:[1,0]
	v_pk_mul_f32 v[18:19], v[18:19], v[202:203] op_sel_hi:[1,0]
	v_pk_mul_f32 v[162:163], v[20:21], v[104:105]
	v_pk_mul_f32 v[164:165], v[22:23], v[106:107]
	v_pk_mul_f32 v[166:167], v[16:17], v[116:117]
	v_pk_mul_f32 v[168:169], v[18:19], v[118:119]
	v_fmac_f32_dpp v162, v20, v100 row_shr:1 row_mask:0xf bank_mask:0xf
	v_fmac_f32_dpp v163, v21, v101 row_shr:1 row_mask:0xf bank_mask:0xf
	v_fmac_f32_dpp v164, v22, v102 row_shr:1 row_mask:0xf bank_mask:0xf
	v_fmac_f32_dpp v165, v23, v103 row_shr:1 row_mask:0xf bank_mask:0xf
	v_fmac_f32_dpp v166, v16, v112 row_shr:1 row_mask:0xf bank_mask:0xf
	v_fmac_f32_dpp v167, v17, v113 row_shr:1 row_mask:0xf bank_mask:0xf
	v_fmac_f32_dpp v168, v18, v114 row_shr:1 row_mask:0xf bank_mask:0xf
	v_fmac_f32_dpp v169, v19, v115 row_shr:1 row_mask:0xf bank_mask:0xf
	v_fmac_f32_dpp v162, v20, v96 row_shr:2 row_mask:0xf bank_mask:0xf
	v_fmac_f32_dpp v163, v21, v97 row_shr:2 row_mask:0xf bank_mask:0xf
	v_fmac_f32_dpp v164, v22, v98 row_shr:2 row_mask:0xf bank_mask:0xf
	v_fmac_f32_dpp v165, v23, v99 row_shr:2 row_mask:0xf bank_mask:0xf
	v_fmac_f32_dpp v166, v16, v108 row_shr:2 row_mask:0xf bank_mask:0xf
	v_fmac_f32_dpp v167, v17, v109 row_shr:2 row_mask:0xf bank_mask:0xf
	v_fmac_f32_dpp v168, v18, v110 row_shr:2 row_mask:0xf bank_mask:0xf
	v_fmac_f32_dpp v169, v19, v111 row_shr:2 row_mask:0xf bank_mask:0xf
	v_fmac_f32_dpp v162, v28, v100 row_shl:15 row_mask:0xf bank_mask:0xf
	v_fmac_f32_dpp v163, v29, v101 row_shl:15 row_mask:0xf bank_mask:0xf
	v_fmac_f32_dpp v164, v30, v102 row_shl:15 row_mask:0xf bank_mask:0xf
	v_fmac_f32_dpp v165, v31, v103 row_shl:15 row_mask:0xf bank_mask:0xf
	v_fmac_f32_dpp v166, v24, v112 row_shl:15 row_mask:0xf bank_mask:0xf
	v_fmac_f32_dpp v167, v25, v113 row_shl:15 row_mask:0xf bank_mask:0xf
	v_fmac_f32_dpp v168, v26, v114 row_shl:15 row_mask:0xf bank_mask:0xf
	v_fmac_f32_dpp v169, v27, v115 row_shl:15 row_mask:0xf bank_mask:0xf
	v_fmac_f32_dpp v162, v28, v96 row_shl:14 row_mask:0xf bank_mask:0xf
	v_fmac_f32_dpp v163, v29, v97 row_shl:14 row_mask:0xf bank_mask:0xf
	v_fmac_f32_dpp v164, v30, v98 row_shl:14 row_mask:0xf bank_mask:0xf
	v_fmac_f32_dpp v165, v31, v99 row_shl:14 row_mask:0xf bank_mask:0xf
	v_fmac_f32_dpp v166, v24, v108 row_shl:14 row_mask:0xf bank_mask:0xf
	v_fmac_f32_dpp v167, v25, v109 row_shl:14 row_mask:0xf bank_mask:0xf
	v_fmac_f32_dpp v168, v26, v110 row_shl:14 row_mask:0xf bank_mask:0xf
	v_fmac_f32_dpp v169, v27, v111 row_shl:14 row_mask:0xf bank_mask:0xf
	v_mul_f32_e32 v230, 0xbfb8aa3b, v162
	v_mul_f32_e32 v231, 0xbfb8aa3b, v163
	v_mul_f32_e32 v232, 0xbfb8aa3b, v164
	v_mul_f32_e32 v233, 0xbfb8aa3b, v165
	v_exp_f32_e32 v230, v230
	v_exp_f32_e32 v231, v231
	v_exp_f32_e32 v232, v232
	v_exp_f32_e32 v233, v233
	v_add_f32_e32 v230, 1.0, v230
	v_add_f32_e32 v231, 1.0, v231
	v_add_f32_e32 v232, 1.0, v232
	v_add_f32_e32 v233, 1.0, v233
	v_rcp_f32_e32 v230, v230
	v_rcp_f32_e32 v231, v231
	v_rcp_f32_e32 v232, v232
	v_rcp_f32_e32 v233, v233
	v_mul_f32_e32 v230, v162, v230
	v_mul_f32_e32 v231, v163, v231
	v_mul_f32_e32 v232, v164, v232
	v_mul_f32_e32 v233, v165, v233
	v_mul_f32_e32 v230, v230, v166
	v_mul_f32_e32 v231, v231, v167
	v_mul_f32_e32 v232, v232, v168
	v_mul_f32_e32 v233, v233, v169
	v_mov_b32_e32 v84, v208
	v_mov_b32_e32 v85, v209
	v_cvt_pk_bf16_f32 v86, v230, v231
	v_cvt_pk_bf16_f32 v87, v232, v233
	s_mov_b32 s8, 0x18c000
	v_lshl_add_u64 v[234:235], v[246:247], 0, s[8:9]
	global_store_dwordx4 v[234:235], v[84:87], off
	v_pk_mul_f32 v[12:13], v[12:13], v[204:205] op_sel_hi:[1,0]
	v_pk_mul_f32 v[14:15], v[14:15], v[204:205] op_sel_hi:[1,0]
	v_pk_mul_f32 v[8:9], v[8:9], v[204:205] op_sel_hi:[1,0]
	v_pk_mul_f32 v[10:11], v[10:11], v[204:205] op_sel_hi:[1,0]
	v_pk_mul_f32 v[162:163], v[12:13], v[104:105]
	v_pk_mul_f32 v[164:165], v[14:15], v[106:107]
	v_pk_mul_f32 v[166:167], v[8:9], v[116:117]
	v_pk_mul_f32 v[168:169], v[10:11], v[118:119]
	v_fmac_f32_dpp v162, v12, v100 row_shr:1 row_mask:0xf bank_mask:0xf
	v_fmac_f32_dpp v163, v13, v101 row_shr:1 row_mask:0xf bank_mask:0xf
	v_fmac_f32_dpp v164, v14, v102 row_shr:1 row_mask:0xf bank_mask:0xf
	v_fmac_f32_dpp v165, v15, v103 row_shr:1 row_mask:0xf bank_mask:0xf
; __device__ __forceinline__ unsigned cvt_pk_bf16(float lo, float hi) { unsigned r; asm volatile("v_cvt_pk_bf16_f32 %0, %1, %2" : "=v"(r) : "v"(lo), "v"(hi)); return r; }
;     static __device__ __forceinline__ float dpp_shr1(float old, float src) { return __builtin_bit_cast(float, __builtin_amdgcn_update_dpp(__builtin_bit_cast(int, old), __builtin_bit_cast(int, src), 0x111, 0xf, 0xf, false)); }
;     static __device__ __forceinline__ float dpp_shr2(float old, float src) { return __builtin_bit_cast(float, __builtin_amdgcn_update_dpp(__builtin_bit_cast(int, old), __builtin_bit_cast(int, src), 0x112, 0xf, 0xf, false)); }
;     static __device__ __forceinline__ float dpp_ror1(float src) { return __builtin_bit_cast(float, __builtin_amdgcn_update_dpp(0, __builtin_bit_cast(int, src), 0x121, 0xf, 0xf, true)); }
;     static __device__ __forceinline__ float dpp_ror2(float src) { return __builtin_bit_cast(float, __builtin_amdgcn_update_dpp(0, __builtin_bit_cast(int, src), 0x122, 0xf, 0xf, true)); }
;     __device__ __forceinline__ void operator()(const f32x4 (&acc)[2][2][4][2], const Unit& u, int wr, int wc, int fr, int fq) const {
;     ...
;                 for (int m = 0; m < 4; ++m) {
;                     f32x4 uu[2];
; #pragma unroll
;                     for (int bj = 0; bj < 2; ++bj) { const f32x4 cur = acc[ai][bj][m][n] * rs[ai][m];
; #pragma unroll
;                         for (int q = 0; q < 4; ++q) { const float p1 = dpp_shr1(o1[bj][q], cur[q]), p2 = dpp_shr2(o2[bj][q], cur[q]);
;                             uu[bj][q] = w[bj][0][q] * p2 + w[bj][1][q] * p1 + w[bj][2][q] * cur[q];
;                             o1[bj][q] = dpp_ror1(cur[q]); o2[bj][q] = dpp_ror2(cur[q]); } }
;                     u32x2v o;
;                     { const float a0 = uu[0][0] * __builtin_amdgcn_rcpf(1.f + __expf(-uu[0][0])) * uu[1][0], a1 = uu[0][1] * __builtin_amdgcn_rcpf(1.f + __expf(-uu[0][1])) * uu[1][1];
;                       const float a2 = uu[0][2] * __builtin_amdgcn_rcpf(1.f + __expf(-uu[0][2])) * uu[1][2], a3 = uu[0][3] * __builtin_amdgcn_rcpf(1.f + __expf(-uu[0][3])) * uu[1][3];
;                       o.x = cvt_pk_bf16(a0, a1); o.y = cvt_pk_bf16(a2, a3); }
;                     *(u32x2v*)(ACT + (size_t)(row0 + ai * HALF + m * 16) * 5632 + u.pn * 128 + cidx + 4 * n) = o;
	v_fmac_f32_dpp v166, v8, v112 row_shr:1 row_mask:0xf bank_mask:0xf
	v_fmac_f32_dpp v167, v9, v113 row_shr:1 row_mask:0xf bank_mask:0xf
	v_fmac_f32_dpp v168, v10, v114 row_shr:1 row_mask:0xf bank_mask:0xf
	v_fmac_f32_dpp v169, v11, v115 row_shr:1 row_mask:0xf bank_mask:0xf
	v_fmac_f32_dpp v162, v12, v96 row_shr:2 row_mask:0xf bank_mask:0xf
	v_fmac_f32_dpp v163, v13, v97 row_shr:2 row_mask:0xf bank_mask:0xf
	v_fmac_f32_dpp v164, v14, v98 row_shr:2 row_mask:0xf bank_mask:0xf
	v_fmac_f32_dpp v165, v15, v99 row_shr:2 row_mask:0xf bank_mask:0xf
	v_fmac_f32_dpp v166, v8, v108 row_shr:2 row_mask:0xf bank_mask:0xf
	v_fmac_f32_dpp v167, v9, v109 row_shr:2 row_mask:0xf bank_mask:0xf
	v_fmac_f32_dpp v168, v10, v110 row_shr:2 row_mask:0xf bank_mask:0xf
	v_fmac_f32_dpp v169, v11, v111 row_shr:2 row_mask:0xf bank_mask:0xf
	v_fmac_f32_dpp v162, v20, v100 row_shl:15 row_mask:0xf bank_mask:0xf
	v_fmac_f32_dpp v163, v21, v101 row_shl:15 row_mask:0xf bank_mask:0xf
	v_fmac_f32_dpp v164, v22, v102 row_shl:15 row_mask:0xf bank_mask:0xf
	v_fmac_f32_dpp v165, v23, v103 row_shl:15 row_mask:0xf bank_mask:0xf
	v_fmac_f32_dpp v166, v16, v112 row_shl:15 row_mask:0xf bank_mask:0xf
	v_fmac_f32_dpp v167, v17, v113 row_shl:15 row_mask:0xf bank_mask:0xf
	v_fmac_f32_dpp v168, v18, v114 row_shl:15 row_mask:0xf bank_mask:0xf
	v_fmac_f32_dpp v169, v19, v115 row_shl:15 row_mask:0xf bank_mask:0xf
	v_fmac_f32_dpp v162, v20, v96 row_shl:14 row_mask:0xf bank_mask:0xf
	v_fmac_f32_dpp v163, v21, v97 row_shl:14 row_mask:0xf bank_mask:0xf
	v_fmac_f32_dpp v164, v22, v98 row_shl:14 row_mask:0xf bank_mask:0xf
	v_fmac_f32_dpp v165, v23, v99 row_shl:14 row_mask:0xf bank_mask:0xf
	v_fmac_f32_dpp v166, v16, v108 row_shl:14 row_mask:0xf bank_mask:0xf
	v_fmac_f32_dpp v167, v17, v109 row_shl:14 row_mask:0xf bank_mask:0xf
	v_fmac_f32_dpp v168, v18, v110 row_shl:14 row_mask:0xf bank_mask:0xf
	v_fmac_f32_dpp v169, v19, v111 row_shl:14 row_mask:0xf bank_mask:0xf
	v_mul_f32_e32 v230, 0xbfb8aa3b, v162
	v_mul_f32_e32 v231, 0xbfb8aa3b, v163
	v_mul_f32_e32 v232, 0xbfb8aa3b, v164
	v_mul_f32_e32 v233, 0xbfb8aa3b, v165
	v_exp_f32_e32 v230, v230
	v_exp_f32_e32 v231, v231
	v_exp_f32_e32 v232, v232
	v_exp_f32_e32 v233, v233
	v_add_f32_e32 v230, 1.0, v230
	v_add_f32_e32 v231, 1.0, v231
	v_add_f32_e32 v232, 1.0, v232
	v_add_f32_e32 v233, 1.0, v233
	v_rcp_f32_e32 v230, v230
	v_rcp_f32_e32 v231, v231
	v_rcp_f32_e32 v232, v232
	v_rcp_f32_e32 v233, v233
	v_mul_f32_e32 v230, v162, v230
	v_mul_f32_e32 v231, v163, v231
	v_mul_f32_e32 v232, v164, v232
	v_mul_f32_e32 v233, v165, v233
	v_mul_f32_e32 v230, v230, v166
	v_mul_f32_e32 v231, v231, v167
	v_mul_f32_e32 v232, v232, v168
	v_mul_f32_e32 v233, v233, v169
	v_mov_b32_e32 v88, v200
	v_mov_b32_e32 v89, v201
	v_cvt_pk_bf16_f32 v90, v230, v231
	v_cvt_pk_bf16_f32 v91, v232, v233
	s_mov_b32 s8, 0x1b8000
	v_lshl_add_u64 v[234:235], v[246:247], 0, s[8:9]
	global_store_dwordx4 v[234:235], v[88:91], off
	v_pk_mul_f32 v[4:5], v[4:5], v[196:197] op_sel_hi:[1,0]
	v_pk_mul_f32 v[6:7], v[6:7], v[196:197] op_sel_hi:[1,0]
	v_pk_mul_f32 v[0:1], v[0:1], v[196:197] op_sel_hi:[1,0]
	v_pk_mul_f32 v[2:3], v[2:3], v[196:197] op_sel_hi:[1,0]
	v_pk_mul_f32 v[162:163], v[4:5], v[104:105]
	v_pk_mul_f32 v[164:165], v[6:7], v[106:107]
	v_pk_mul_f32 v[166:167], v[0:1], v[116:117]
	v_pk_mul_f32 v[168:169], v[2:3], v[118:119]
	v_fmac_f32_dpp v162, v4, v100 row_shr:1 row_mask:0xf bank_mask:0xf
	v_fmac_f32_dpp v163, v5, v101 row_shr:1 row_mask:0xf bank_mask:0xf
	v_fmac_f32_dpp v164, v6, v102 row_shr:1 row_mask:0xf bank_mask:0xf
	v_fmac_f32_dpp v165, v7, v103 row_shr:1 row_mask:0xf bank_mask:0xf
	v_fmac_f32_dpp v166, v0, v112 row_shr:1 row_mask:0xf bank_mask:0xf
	v_fmac_f32_dpp v167, v1, v113 row_shr:1 row_mask:0xf bank_mask:0xf
	v_fmac_f32_dpp v168, v2, v114 row_shr:1 row_mask:0xf bank_mask:0xf
	v_fmac_f32_dpp v169, v3, v115 row_shr:1 row_mask:0xf bank_mask:0xf
	v_fmac_f32_dpp v162, v4, v96 row_shr:2 row_mask:0xf bank_mask:0xf
	v_fmac_f32_dpp v163, v5, v97 row_shr:2 row_mask:0xf bank_mask:0xf
	v_fmac_f32_dpp v164, v6, v98 row_shr:2 row_mask:0xf bank_mask:0xf
	v_fmac_f32_dpp v165, v7, v99 row_shr:2 row_mask:0xf bank_mask:0xf
	v_fmac_f32_dpp v166, v0, v108 row_shr:2 row_mask:0xf bank_mask:0xf
	v_fmac_f32_dpp v167, v1, v109 row_shr:2 row_mask:0xf bank_mask:0xf
	v_fmac_f32_dpp v168, v2, v110 row_shr:2 row_mask:0xf bank_mask:0xf
	v_fmac_f32_dpp v169, v3, v111 row_shr:2 row_mask:0xf bank_mask:0xf
	v_fmac_f32_dpp v162, v12, v100 row_shl:15 row_mask:0xf bank_mask:0xf
	v_fmac_f32_dpp v163, v13, v101 row_shl:15 row_mask:0xf bank_mask:0xf
	v_fmac_f32_dpp v164, v14, v102 row_shl:15 row_mask:0xf bank_mask:0xf
	v_fmac_f32_dpp v165, v15, v103 row_shl:15 row_mask:0xf bank_mask:0xf
	v_fmac_f32_dpp v166, v8, v112 row_shl:15 row_mask:0xf bank_mask:0xf
	v_fmac_f32_dpp v167, v9, v113 row_shl:15 row_mask:0xf bank_mask:0xf
	v_fmac_f32_dpp v168, v10, v114 row_shl:15 row_mask:0xf bank_mask:0xf
	v_fmac_f32_dpp v169, v11, v115 row_shl:15 row_mask:0xf bank_mask:0xf
	v_fmac_f32_dpp v162, v12, v96 row_shl:14 row_mask:0xf bank_mask:0xf
	v_fmac_f32_dpp v163, v13, v97 row_shl:14 row_mask:0xf bank_mask:0xf
	v_fmac_f32_dpp v164, v14, v98 row_shl:14 row_mask:0xf bank_mask:0xf
	v_fmac_f32_dpp v165, v15, v99 row_shl:14 row_mask:0xf bank_mask:0xf
	v_fmac_f32_dpp v166, v8, v108 row_shl:14 row_mask:0xf bank_mask:0xf
	v_fmac_f32_dpp v167, v9, v109 row_shl:14 row_mask:0xf bank_mask:0xf
	v_fmac_f32_dpp v168, v10, v110 row_shl:14 row_mask:0xf bank_mask:0xf
	v_fmac_f32_dpp v169, v11, v111 row_shl:14 row_mask:0xf bank_mask:0xf
	v_mul_f32_e32 v230, 0xbfb8aa3b, v162
	v_mul_f32_e32 v231, 0xbfb8aa3b, v163
	v_mul_f32_e32 v232, 0xbfb8aa3b, v164
	v_mul_f32_e32 v233, 0xbfb8aa3b, v165
	v_exp_f32_e32 v230, v230
	v_exp_f32_e32 v231, v231
	v_exp_f32_e32 v232, v232
	v_exp_f32_e32 v233, v233
	v_add_f32_e32 v230, 1.0, v230
	v_add_f32_e32 v231, 1.0, v231
	v_add_f32_e32 v232, 1.0, v232
	v_add_f32_e32 v233, 1.0, v233
	v_rcp_f32_e32 v230, v230
	v_rcp_f32_e32 v231, v231
	v_rcp_f32_e32 v232, v232
	v_rcp_f32_e32 v233, v233
	v_mul_f32_e32 v230, v162, v230
	v_mul_f32_e32 v231, v163, v231
	v_mul_f32_e32 v232, v164, v232
	v_mul_f32_e32 v233, v165, v233
	v_mul_f32_e32 v230, v230, v166
	v_mul_f32_e32 v231, v231, v167
	v_mul_f32_e32 v232, v232, v168
	v_mul_f32_e32 v233, v233, v169
	v_mov_b32_e32 v92, v248
	v_mov_b32_e32 v93, v249
	v_cvt_pk_bf16_f32 v94, v230, v231
	v_cvt_pk_bf16_f32 v95, v232, v233
	s_mov_b32 s8, 0x1e4000
	v_lshl_add_u64 v[234:235], v[246:247], 0, s[8:9]
	global_store_dwordx4 v[234:235], v[92:95], off
	s_andn2_b64 vcc, exec, s[6:7]
	s_mov_b64 s[6:7], -1
	s_cbranch_vccnz .LBB0_1881
	v_readlane_b32 s6, v255, 11
	v_readlane_b32 s7, v255, 12
	s_andn2_b64 vcc, exec, s[6:7]
	s_cbranch_vccnz .LBB0_1880
	s_barrier
	s_branch .LBB0_1880
